# v11: v10b + K-loop LDS-DMA loads in SGPR-base + 32-bit lane-offset form (no 64-bit VALU address add)
# speedup vs baseline: 1.0056x; 1.0056x over previous
; #define PG8_STAGE(bufoff, gbase, voff) do { _Pragma("unroll") for (int _i = 0; _i < 2; ++_i) \
;         __builtin_amdgcn_global_load_lds((const unsigned*)((const char*)(gbase) + (voff)[_i]), (PG8_LAS unsigned*)(lds + (bufoff) + ldsw + _i * 8192), 16, 0, 0); } while (0)
; #define PG8_LDA(dst, b, h) do { _Pragma("unroll") for (int m = 0; m < 4; ++m) _Pragma("unroll") for (int k = 0; k < 2; ++k) dst[m][k] = *(const PG8_LAS bf16x8*)(lds + PG8_SA(b, h) + aoff + m * 2048 + k * 1024); } while (0)
; #define PG8_LDB(dst, b, h) do { _Pragma("unroll") for (int n = 0; n < 2; ++n) _Pragma("unroll") for (int k = 0; k < 2; ++k) dst[n][k] = *(const PG8_LAS bf16x8*)(lds + PG8_SB(b, h) + boff + n * 2048 + k * 1024); } while (0)
; #define PG8_MMA(ai, bj, At, Bt) do { __builtin_amdgcn_s_setprio(1); _Pragma("unroll") for (int m = 0; m < 4; ++m) _Pragma("unroll") for (int n = 0; n < 2; ++n) _Pragma("unroll") for (int k = 0; k < 2; ++k) \
;         acc[ai][bj][m][n] = __builtin_amdgcn_mfma_f32_16x16x32_bf16(Bt[n][k], At[m][k], acc[ai][bj][m][n], 0, 0, 0); __builtin_amdgcn_s_setprio(0); } while (0)
; #define PG8_WAIT_V(n) asm volatile("s_waitcnt vmcnt(" #n ")" ::: "memory")
; #define PG8_WAIT_L(n) asm volatile("s_waitcnt lgkmcnt(" #n ")" ::: "memory")
; template <class Epi, class Sched, bool ALIGN_EPI = false, bool SP2 = false>
; __device__ __forceinline__ void gemm_phase(PG8_LAS unsigned char* lds, const Gemm g, const Sched& S, const Epi& E) {
;     ...
;             const bool last = (t == nt - 2);
;             const char* a1 = cA + (size_t)(t + 1) * kstep;
;             const char* a2 = last ? nA : cA + (size_t)(t + 2) * kstep; const char* b2 = last ? nB : cB + (size_t)(t + 2) * kstep;
;             const char* a3 = a2 + kstep; const char* b3 = b2 + kstep;
;             if (last && has_next) S.a_ready(nxt);
;             if constexpr (SP2) {
;             PG8_LDB(B0, 0, 0); PG8_LDB(B1, 0, 1); PG8_SCHED; PG8_LDA(At, 0, 0); PG8_STAGE(PG8_SA(1, 1), a1 + hstep, voffA);
;             PG8_WAIT_V(8); PG8_WAIT_L(0); PG8_BAR; PG8_MMA(0, 0, At, B0); PG8_MMA(0, 1, At, B1); PG8_BAR; PG8_SCHED;
;             PG8_LDA(At, 0, 1); PG8_STAGE(PG8_SB(0, 0), b2, voffB); PG8_STAGE(PG8_SB(0, 1), b2 + hstep, voffB); PG8_STAGE(PG8_SA(0, 0), a2, voffA);
;             PG8_WAIT_V(8); PG8_WAIT_L(0); PG8_BAR; PG8_MMA(1, 0, At, B0); PG8_MMA(1, 1, At, B1); PG8_BAR; PG8_SCHED;
.LBB0_115:
	ds_read_b128 v[154:157], v150
	ds_read_b128 v[158:161], v150 offset:1024
	ds_read_b128 v[162:165], v150 offset:2048
	ds_read_b128 v[166:169], v150 offset:3072
	ds_read_b128 v[170:173], v151
	ds_read_b128 v[174:177], v151 offset:1024
	ds_read_b128 v[180:183], v151 offset:2048
	ds_read_b128 v[184:187], v151 offset:3072
	s_add_u32 s50, s48, 0x4000
	s_addc_u32 s51, s49, 0
	s_cmp_eq_u32 s76, 60
	s_cselect_b32 s74, s64, s50
	s_cselect_b32 s75, s25, s51
	s_cselect_b32 s72, s65, s68
	s_cselect_b32 s73, s19, s69
	s_add_u32 s50, s74, 0x8000
	s_addc_u32 s51, s75, 0
	s_sub_u32 s50, s48, 0x4000
	s_subb_u32 s51, s49, 0
	s_mov_b32 m0, s58
	s_nop 0
	global_load_lds_dwordx4 v130, s[50:51]
	s_mov_b32 m0, s59
	s_nop 0
	global_load_lds_dwordx4 v134, s[50:51]
	s_add_i32 m0, s28, 0xc000
	ds_read_b128 v[188:191], v152
	ds_read_b128 v[196:199], v152 offset:1024
	ds_read_b128 v[200:203], v152 offset:2048
	ds_read_b128 v[204:207], v152 offset:3072
	ds_read_b128 v[208:211], v152 offset:4096
	ds_read_b128 v[212:215], v152 offset:5120
	ds_read_b128 v[216:219], v152 offset:6144
	ds_read_b128 v[220:223], v152 offset:7168
	global_load_lds_dwordx4 v140, s[48:49]
	s_add_i32 m0, s28, 0xe000
	s_nop 0
	global_load_lds_dwordx4 v142, s[48:49]
	s_waitcnt vmcnt(8)
	s_waitcnt lgkmcnt(0)
	s_barrier
	s_setprio 1
	s_waitcnt lgkmcnt(0)
	v_mfma_f32_16x16x32_bf16 v[126:129], v[154:157], v[188:191], v[126:129]
	v_mfma_f32_16x16x32_bf16 v[126:129], v[158:161], v[196:199], v[126:129]
	v_mfma_f32_16x16x32_bf16 v[110:113], v[154:157], v[200:203], v[110:113]
	v_mfma_f32_16x16x32_bf16 v[110:113], v[158:161], v[204:207], v[110:113]
	v_mfma_f32_16x16x32_bf16 v[94:97], v[154:157], v[208:211], v[94:97]
	v_mfma_f32_16x16x32_bf16 v[94:97], v[158:161], v[212:215], v[94:97]
	v_mfma_f32_16x16x32_bf16 v[78:81], v[154:157], v[216:219], v[78:81]
	v_mfma_f32_16x16x32_bf16 v[78:81], v[158:161], v[220:223], v[78:81]
	v_mfma_f32_16x16x32_bf16 v[118:121], v[162:165], v[188:191], v[118:121]
	v_mfma_f32_16x16x32_bf16 v[118:121], v[166:169], v[196:199], v[118:121]
	v_mfma_f32_16x16x32_bf16 v[102:105], v[162:165], v[200:203], v[102:105]
	v_mfma_f32_16x16x32_bf16 v[102:105], v[166:169], v[204:207], v[102:105]
	v_mfma_f32_16x16x32_bf16 v[86:89], v[162:165], v[208:211], v[86:89]
	v_mfma_f32_16x16x32_bf16 v[86:89], v[166:169], v[212:215], v[86:89]
	v_mfma_f32_16x16x32_bf16 v[70:73], v[162:165], v[216:219], v[70:73]
	v_mfma_f32_16x16x32_bf16 v[70:73], v[166:169], v[220:223], v[70:73]
	s_setprio 0
	s_setprio 1
	v_mfma_f32_16x16x32_bf16 v[122:125], v[170:173], v[188:191], v[122:125]
	v_mfma_f32_16x16x32_bf16 v[122:125], v[174:177], v[196:199], v[122:125]
	v_mfma_f32_16x16x32_bf16 v[106:109], v[170:173], v[200:203], v[106:109]
	v_mfma_f32_16x16x32_bf16 v[106:109], v[174:177], v[204:207], v[106:109]
	v_mfma_f32_16x16x32_bf16 v[90:93], v[170:173], v[208:211], v[90:93]
	v_mfma_f32_16x16x32_bf16 v[90:93], v[174:177], v[212:215], v[90:93]
	v_mfma_f32_16x16x32_bf16 v[74:77], v[170:173], v[216:219], v[74:77]
	v_mfma_f32_16x16x32_bf16 v[74:77], v[174:177], v[220:223], v[74:77]
	v_mfma_f32_16x16x32_bf16 v[114:117], v[180:183], v[188:191], v[114:117]
	v_mfma_f32_16x16x32_bf16 v[114:117], v[184:187], v[196:199], v[114:117]
	v_mfma_f32_16x16x32_bf16 v[98:101], v[180:183], v[200:203], v[98:101]
	v_mfma_f32_16x16x32_bf16 v[98:101], v[184:187], v[204:207], v[98:101]
	v_mfma_f32_16x16x32_bf16 v[82:85], v[180:183], v[208:211], v[82:85]
	v_mfma_f32_16x16x32_bf16 v[82:85], v[184:187], v[212:215], v[82:85]
	v_mfma_f32_16x16x32_bf16 v[66:69], v[180:183], v[216:219], v[66:69]
	v_mfma_f32_16x16x32_bf16 v[66:69], v[184:187], v[220:223], v[66:69]
	s_setprio 0
	s_barrier
	s_add_i32 s77, s61, s3
	s_mov_b32 m0, s77
	ds_read_b128 v[188:191], v152 offset:16384
	ds_read_b128 v[196:199], v152 offset:17408
	ds_read_b128 v[200:203], v152 offset:18432
	ds_read_b128 v[204:207], v152 offset:19456
	ds_read_b128 v[208:211], v152 offset:20480
	ds_read_b128 v[212:215], v152 offset:21504
	ds_read_b128 v[216:219], v152 offset:22528
	ds_read_b128 v[220:223], v152 offset:23552
	global_load_lds_dwordx4 v132, s[72:73]
	s_add_i32 m0, s77, 0x2000
	s_add_u32 s78, s72, 0x4000
	v_lshl_add_u64 v[224:225], s[72:73], 0, v[136:137]
	s_addc_u32 s79, s73, 0
	s_add_i32 s77, s62, s3
	global_load_lds_dwordx4 v[224:225], off
	s_mov_b32 m0, s77
	s_nop 0
	global_load_lds_dwordx4 v132, s[78:79]
	s_add_i32 m0, s77, 0x2000
	s_nop 0
	global_load_lds_dwordx4 v136, s[78:79]
	s_waitcnt vmcnt(6)
	s_waitcnt lgkmcnt(0)
	s_barrier
	s_setprio 1
	s_waitcnt lgkmcnt(0)
	v_mfma_f32_16x16x32_bf16 v[62:65], v[154:157], v[188:191], v[62:65]
	v_mfma_f32_16x16x32_bf16 v[62:65], v[158:161], v[196:199], v[62:65]
	v_mfma_f32_16x16x32_bf16 v[46:49], v[154:157], v[200:203], v[46:49]
	v_mfma_f32_16x16x32_bf16 v[46:49], v[158:161], v[204:207], v[46:49]
	v_mfma_f32_16x16x32_bf16 v[30:33], v[154:157], v[208:211], v[30:33]
	v_mfma_f32_16x16x32_bf16 v[30:33], v[158:161], v[212:215], v[30:33]
	v_mfma_f32_16x16x32_bf16 v[14:17], v[154:157], v[216:219], v[14:17]
	v_mfma_f32_16x16x32_bf16 v[14:17], v[158:161], v[220:223], v[14:17]
	v_mfma_f32_16x16x32_bf16 v[54:57], v[162:165], v[188:191], v[54:57]
	v_mfma_f32_16x16x32_bf16 v[54:57], v[166:169], v[196:199], v[54:57]
	v_mfma_f32_16x16x32_bf16 v[38:41], v[162:165], v[200:203], v[38:41]
	v_mfma_f32_16x16x32_bf16 v[38:41], v[166:169], v[204:207], v[38:41]
	v_mfma_f32_16x16x32_bf16 v[22:25], v[162:165], v[208:211], v[22:25]
	v_mfma_f32_16x16x32_bf16 v[22:25], v[166:169], v[212:215], v[22:25]
	v_mfma_f32_16x16x32_bf16 v[6:9], v[162:165], v[216:219], v[6:9]
	v_mfma_f32_16x16x32_bf16 v[6:9], v[166:169], v[220:223], v[6:9]
	s_setprio 0
	s_setprio 1
	v_mfma_f32_16x16x32_bf16 v[58:61], v[170:173], v[188:191], v[58:61]
	v_mfma_f32_16x16x32_bf16 v[58:61], v[174:177], v[196:199], v[58:61]
	v_mfma_f32_16x16x32_bf16 v[42:45], v[170:173], v[200:203], v[42:45]
	v_mfma_f32_16x16x32_bf16 v[42:45], v[174:177], v[204:207], v[42:45]
	v_mfma_f32_16x16x32_bf16 v[26:29], v[170:173], v[208:211], v[26:29]
	v_mfma_f32_16x16x32_bf16 v[26:29], v[174:177], v[212:215], v[26:29]
	v_mfma_f32_16x16x32_bf16 v[10:13], v[170:173], v[216:219], v[10:13]
	v_mfma_f32_16x16x32_bf16 v[10:13], v[174:177], v[220:223], v[10:13]
	v_mfma_f32_16x16x32_bf16 v[50:53], v[180:183], v[188:191], v[50:53]
	v_mfma_f32_16x16x32_bf16 v[50:53], v[184:187], v[196:199], v[50:53]
	v_mfma_f32_16x16x32_bf16 v[34:37], v[180:183], v[200:203], v[34:37]
	v_mfma_f32_16x16x32_bf16 v[34:37], v[184:187], v[204:207], v[34:37]
	v_mfma_f32_16x16x32_bf16 v[18:21], v[180:183], v[208:211], v[18:21]
	v_mfma_f32_16x16x32_bf16 v[18:21], v[184:187], v[212:215], v[18:21]
	v_mfma_f32_16x16x32_bf16 v[2:5], v[180:183], v[216:219], v[2:5]
	v_mfma_f32_16x16x32_bf16 v[2:5], v[184:187], v[220:223], v[2:5]
	s_setprio 0
	s_barrier
; #define PG8_STAGE(bufoff, gbase, voff) do { _Pragma("unroll") for (int _i = 0; _i < 2; ++_i) \
;         __builtin_amdgcn_global_load_lds((const unsigned*)((const char*)(gbase) + (voff)[_i]), (PG8_LAS unsigned*)(lds + (bufoff) + ldsw + _i * 8192), 16, 0, 0); } while (0)
; #define PG8_LDA(dst, b, h) do { _Pragma("unroll") for (int m = 0; m < 4; ++m) _Pragma("unroll") for (int k = 0; k < 2; ++k) dst[m][k] = *(const PG8_LAS bf16x8*)(lds + PG8_SA(b, h) + aoff + m * 2048 + k * 1024); } while (0)
; #define PG8_LDB(dst, b, h) do { _Pragma("unroll") for (int n = 0; n < 2; ++n) _Pragma("unroll") for (int k = 0; k < 2; ++k) dst[n][k] = *(const PG8_LAS bf16x8*)(lds + PG8_SB(b, h) + boff + n * 2048 + k * 1024); } while (0)
; #define PG8_MMA(ai, bj, At, Bt) do { __builtin_amdgcn_s_setprio(1); _Pragma("unroll") for (int m = 0; m < 4; ++m) _Pragma("unroll") for (int n = 0; n < 2; ++n) _Pragma("unroll") for (int k = 0; k < 2; ++k) \
;         acc[ai][bj][m][n] = __builtin_amdgcn_mfma_f32_16x16x32_bf16(Bt[n][k], At[m][k], acc[ai][bj][m][n], 0, 0, 0); __builtin_amdgcn_s_setprio(0); } while (0)
; #define PG8_WAIT_V(n) asm volatile("s_waitcnt vmcnt(" #n ")" ::: "memory")
; #define PG8_WAIT_L(n) asm volatile("s_waitcnt lgkmcnt(" #n ")" ::: "memory")
; #define PG8_BAR __builtin_amdgcn_s_barrier()
; #define PG8_SCHED __builtin_amdgcn_sched_barrier(0)
; template <class Epi, class Sched, bool ALIGN_EPI = false, bool SP2 = false>
; __device__ __forceinline__ void gemm_phase(PG8_LAS unsigned char* lds, const Gemm g, const Sched& S, const Epi& E) {
;     ...
;             PG8_LDB(B0, 1, 0); PG8_LDB(B1, 1, 1); PG8_SCHED; PG8_LDA(At, 1, 0); PG8_STAGE(PG8_SA(0, 1), a2 + hstep, voffA);
;             PG8_WAIT_V(8); PG8_WAIT_L(0); PG8_BAR; PG8_MMA(0, 0, At, B0); PG8_MMA(0, 1, At, B1); PG8_BAR; PG8_SCHED;
;             PG8_LDA(At, 1, 1); PG8_STAGE(PG8_SB(1, 0), b3, voffB); PG8_STAGE(PG8_SB(1, 1), b3 + hstep, voffB); PG8_STAGE(PG8_SA(1, 0), a3, voffA);
;             PG8_WAIT_V(8); PG8_WAIT_L(0); PG8_BAR; PG8_MMA(1, 0, At, B0); PG8_MMA(1, 1, At, B1); PG8_BAR; PG8_SCHED;
	s_add_i32 s77, 0, 0x18000
	v_add_u32_e32 v138, s77, v148
	s_add_i32 s78, 0, 0x1c000
	ds_read_b128 v[154:157], v138
	ds_read_b128 v[158:161], v138 offset:1024
	ds_read_b128 v[162:165], v138 offset:2048
	ds_read_b128 v[166:169], v138 offset:3072
	v_add_u32_e32 v138, s78, v148
	ds_read_b128 v[170:173], v138
	ds_read_b128 v[174:177], v138 offset:1024
	ds_read_b128 v[180:183], v138 offset:2048
	ds_read_b128 v[184:187], v138 offset:3072
	s_mov_b32 m0, s28
	s_nop 0
	global_load_lds_dwordx4 v130, s[74:75]
	s_mov_b32 m0, s29
	s_nop 0
	global_load_lds_dwordx4 v134, s[74:75]
	s_add_u32 s74, s74, 0x4000
	s_addc_u32 s75, s75, 0
	s_mov_b32 m0, s30
	ds_read_b128 v[188:191], v152 offset:32768
	ds_read_b128 v[196:199], v152 offset:33792
	ds_read_b128 v[200:203], v152 offset:34816
	ds_read_b128 v[204:207], v152 offset:35840
	ds_read_b128 v[208:211], v152 offset:36864
	ds_read_b128 v[212:215], v152 offset:37888
	ds_read_b128 v[216:219], v152 offset:38912
	ds_read_b128 v[220:223], v152 offset:39936
	global_load_lds_dwordx4 v130, s[74:75]
	s_mov_b32 m0, s31
	s_nop 0
	global_load_lds_dwordx4 v134, s[74:75]
	s_waitcnt vmcnt(8)
	s_waitcnt lgkmcnt(0)
	s_barrier
	s_setprio 1
	s_waitcnt lgkmcnt(0)
	v_mfma_f32_16x16x32_bf16 v[126:129], v[154:157], v[188:191], v[126:129]
	v_mfma_f32_16x16x32_bf16 v[126:129], v[158:161], v[196:199], v[126:129]
	v_mfma_f32_16x16x32_bf16 v[110:113], v[154:157], v[200:203], v[110:113]
	v_mfma_f32_16x16x32_bf16 v[110:113], v[158:161], v[204:207], v[110:113]
	v_mfma_f32_16x16x32_bf16 v[94:97], v[154:157], v[208:211], v[94:97]
	v_mfma_f32_16x16x32_bf16 v[94:97], v[158:161], v[212:215], v[94:97]
	v_mfma_f32_16x16x32_bf16 v[78:81], v[154:157], v[216:219], v[78:81]
	v_mfma_f32_16x16x32_bf16 v[78:81], v[158:161], v[220:223], v[78:81]
	v_mfma_f32_16x16x32_bf16 v[118:121], v[162:165], v[188:191], v[118:121]
	v_mfma_f32_16x16x32_bf16 v[118:121], v[166:169], v[196:199], v[118:121]
	v_mfma_f32_16x16x32_bf16 v[102:105], v[162:165], v[200:203], v[102:105]
	v_mfma_f32_16x16x32_bf16 v[102:105], v[166:169], v[204:207], v[102:105]
	v_mfma_f32_16x16x32_bf16 v[86:89], v[162:165], v[208:211], v[86:89]
	v_mfma_f32_16x16x32_bf16 v[86:89], v[166:169], v[212:215], v[86:89]
	v_mfma_f32_16x16x32_bf16 v[70:73], v[162:165], v[216:219], v[70:73]
	v_mfma_f32_16x16x32_bf16 v[70:73], v[166:169], v[220:223], v[70:73]
	s_setprio 0
	s_setprio 1
	v_mfma_f32_16x16x32_bf16 v[122:125], v[170:173], v[188:191], v[122:125]
	v_mfma_f32_16x16x32_bf16 v[122:125], v[174:177], v[196:199], v[122:125]
	v_mfma_f32_16x16x32_bf16 v[106:109], v[170:173], v[200:203], v[106:109]
	v_mfma_f32_16x16x32_bf16 v[106:109], v[174:177], v[204:207], v[106:109]
	v_mfma_f32_16x16x32_bf16 v[90:93], v[170:173], v[208:211], v[90:93]
	v_mfma_f32_16x16x32_bf16 v[90:93], v[174:177], v[212:215], v[90:93]
	v_mfma_f32_16x16x32_bf16 v[74:77], v[170:173], v[216:219], v[74:77]
	v_mfma_f32_16x16x32_bf16 v[74:77], v[174:177], v[220:223], v[74:77]
	v_mfma_f32_16x16x32_bf16 v[114:117], v[180:183], v[188:191], v[114:117]
	v_mfma_f32_16x16x32_bf16 v[114:117], v[184:187], v[196:199], v[114:117]
	v_mfma_f32_16x16x32_bf16 v[98:101], v[180:183], v[200:203], v[98:101]
	v_mfma_f32_16x16x32_bf16 v[98:101], v[184:187], v[204:207], v[98:101]
	v_mfma_f32_16x16x32_bf16 v[82:85], v[180:183], v[208:211], v[82:85]
	v_mfma_f32_16x16x32_bf16 v[82:85], v[184:187], v[212:215], v[82:85]
	v_mfma_f32_16x16x32_bf16 v[66:69], v[180:183], v[216:219], v[66:69]
	v_mfma_f32_16x16x32_bf16 v[66:69], v[184:187], v[220:223], v[66:69]
	s_setprio 0
	s_barrier
	s_add_u32 s74, s72, 0x8000
	s_addc_u32 s75, s73, 0
	s_add_i32 s77, s77, s3
	s_mov_b32 m0, s77
	ds_read_b128 v[188:191], v152 offset:49152
	ds_read_b128 v[196:199], v152 offset:50176
	ds_read_b128 v[200:203], v152 offset:51200
	ds_read_b128 v[204:207], v152 offset:52224
	ds_read_b128 v[208:211], v152 offset:53248
	ds_read_b128 v[212:215], v152 offset:54272
	ds_read_b128 v[216:219], v152 offset:55296
	ds_read_b128 v[220:223], v152 offset:56320
	global_load_lds_dwordx4 v132, s[74:75]
	s_add_i32 m0, s77, 0x2000
	s_add_u32 s72, s72, 0xc000
	v_lshl_add_u64 v[224:225], s[74:75], 0, v[136:137]
	s_addc_u32 s73, s73, 0
	s_add_i32 s74, s78, s3
	global_load_lds_dwordx4 v[224:225], off
	s_mov_b32 m0, s74
	s_nop 0
	global_load_lds_dwordx4 v132, s[72:73]
	s_add_i32 m0, s74, 0x2000
	s_nop 0
	global_load_lds_dwordx4 v136, s[72:73]
	s_waitcnt vmcnt(6)
	s_waitcnt lgkmcnt(0)
	s_barrier
	s_setprio 1
	s_waitcnt lgkmcnt(0)
	v_mfma_f32_16x16x32_bf16 v[62:65], v[154:157], v[188:191], v[62:65]
	v_mfma_f32_16x16x32_bf16 v[62:65], v[158:161], v[196:199], v[62:65]
	v_mfma_f32_16x16x32_bf16 v[46:49], v[154:157], v[200:203], v[46:49]
	v_mfma_f32_16x16x32_bf16 v[46:49], v[158:161], v[204:207], v[46:49]
	v_mfma_f32_16x16x32_bf16 v[30:33], v[154:157], v[208:211], v[30:33]
	v_mfma_f32_16x16x32_bf16 v[30:33], v[158:161], v[212:215], v[30:33]
	v_mfma_f32_16x16x32_bf16 v[14:17], v[154:157], v[216:219], v[14:17]
	v_mfma_f32_16x16x32_bf16 v[14:17], v[158:161], v[220:223], v[14:17]
	v_mfma_f32_16x16x32_bf16 v[54:57], v[162:165], v[188:191], v[54:57]
	v_mfma_f32_16x16x32_bf16 v[54:57], v[166:169], v[196:199], v[54:57]
	v_mfma_f32_16x16x32_bf16 v[38:41], v[162:165], v[200:203], v[38:41]
	v_mfma_f32_16x16x32_bf16 v[38:41], v[166:169], v[204:207], v[38:41]
	v_mfma_f32_16x16x32_bf16 v[22:25], v[162:165], v[208:211], v[22:25]
	v_mfma_f32_16x16x32_bf16 v[22:25], v[166:169], v[212:215], v[22:25]
	v_mfma_f32_16x16x32_bf16 v[6:9], v[162:165], v[216:219], v[6:9]
	v_mfma_f32_16x16x32_bf16 v[6:9], v[166:169], v[220:223], v[6:9]
	s_setprio 0
	s_setprio 1
	v_mfma_f32_16x16x32_bf16 v[58:61], v[170:173], v[188:191], v[58:61]
	v_mfma_f32_16x16x32_bf16 v[58:61], v[174:177], v[196:199], v[58:61]
	v_mfma_f32_16x16x32_bf16 v[42:45], v[170:173], v[200:203], v[42:45]
	v_mfma_f32_16x16x32_bf16 v[42:45], v[174:177], v[204:207], v[42:45]
	v_mfma_f32_16x16x32_bf16 v[26:29], v[170:173], v[208:211], v[26:29]
	v_mfma_f32_16x16x32_bf16 v[26:29], v[174:177], v[212:215], v[26:29]
	v_mfma_f32_16x16x32_bf16 v[10:13], v[170:173], v[216:219], v[10:13]
	v_mfma_f32_16x16x32_bf16 v[10:13], v[174:177], v[220:223], v[10:13]
	v_mfma_f32_16x16x32_bf16 v[50:53], v[180:183], v[188:191], v[50:53]
	v_mfma_f32_16x16x32_bf16 v[50:53], v[184:187], v[196:199], v[50:53]
	v_mfma_f32_16x16x32_bf16 v[34:37], v[180:183], v[200:203], v[34:37]
	v_mfma_f32_16x16x32_bf16 v[34:37], v[184:187], v[204:207], v[34:37]
	v_mfma_f32_16x16x32_bf16 v[18:21], v[180:183], v[208:211], v[18:21]
	v_mfma_f32_16x16x32_bf16 v[18:21], v[184:187], v[212:215], v[18:21]
	v_mfma_f32_16x16x32_bf16 v[2:5], v[180:183], v[216:219], v[2:5]
	v_mfma_f32_16x16x32_bf16 v[2:5], v[184:187], v[220:223], v[2:5]
	s_setprio 0
	s_barrier
	s_add_i32 s76, s76, 2
	s_add_u32 s48, s48, 0x10000
	s_addc_u32 s49, s49, 0
	s_add_u32 s68, s68, 0x10000
	s_addc_u32 s69, s69, 0
	s_cmp_gt_u32 s76, 61
	s_cbranch_scc0 .LBB0_115
	s_and_b64 vcc, exec, s[14:15]
	s_cbranch_vccz .LBB0_118
	s_barrier

; #define PG8_STAGE(bufoff, gbase, voff) do { _Pragma("unroll") for (int _i = 0; _i < 2; ++_i) \
;         __builtin_amdgcn_global_load_lds((const unsigned*)((const char*)(gbase) + (voff)[_i]), (PG8_LAS unsigned*)(lds + (bufoff) + ldsw + _i * 8192), 16, 0, 0); } while (0)
; #define PG8_LDA(dst, b, h) do { _Pragma("unroll") for (int m = 0; m < 4; ++m) _Pragma("unroll") for (int k = 0; k < 2; ++k) dst[m][k] = *(const PG8_LAS bf16x8*)(lds + PG8_SA(b, h) + aoff + m * 2048 + k * 1024); } while (0)
; #define PG8_LDB(dst, b, h) do { _Pragma("unroll") for (int n = 0; n < 2; ++n) _Pragma("unroll") for (int k = 0; k < 2; ++k) dst[n][k] = *(const PG8_LAS bf16x8*)(lds + PG8_SB(b, h) + boff + n * 2048 + k * 1024); } while (0)
; #define PG8_MMA(ai, bj, At, Bt) do { __builtin_amdgcn_s_setprio(1); _Pragma("unroll") for (int m = 0; m < 4; ++m) _Pragma("unroll") for (int n = 0; n < 2; ++n) _Pragma("unroll") for (int k = 0; k < 2; ++k) \
;         acc[ai][bj][m][n] = __builtin_amdgcn_mfma_f32_16x16x32_bf16(Bt[n][k], At[m][k], acc[ai][bj][m][n], 0, 0, 0); __builtin_amdgcn_s_setprio(0); } while (0)
; #define PG8_WAIT_V(n) asm volatile("s_waitcnt vmcnt(" #n ")" ::: "memory")
; #define PG8_WAIT_L(n) asm volatile("s_waitcnt lgkmcnt(" #n ")" ::: "memory")
; template <class Epi, class Sched, bool ALIGN_EPI = false, bool SP2 = false>
; __device__ __forceinline__ void gemm_phase(PG8_LAS unsigned char* lds, const Gemm g, const Sched& S, const Epi& E) {
;     ...
;             const bool last = (t == nt - 2);
;             const char* a1 = cA + (size_t)(t + 1) * kstep;
;             const char* a2 = last ? nA : cA + (size_t)(t + 2) * kstep; const char* b2 = last ? nB : cB + (size_t)(t + 2) * kstep;
;             const char* a3 = a2 + kstep; const char* b3 = b2 + kstep;
;             if (last && has_next) S.a_ready(nxt);
;             if constexpr (SP2) {
;             PG8_LDB(B0, 0, 0); PG8_LDB(B1, 0, 1); PG8_SCHED; PG8_LDA(At, 0, 0); PG8_STAGE(PG8_SA(1, 1), a1 + hstep, voffA);
;             PG8_WAIT_V(8); PG8_WAIT_L(0); PG8_BAR; PG8_MMA(0, 0, At, B0); PG8_MMA(0, 1, At, B1); PG8_BAR; PG8_SCHED;
;             PG8_LDA(At, 0, 1); PG8_STAGE(PG8_SB(0, 0), b2, voffB); PG8_STAGE(PG8_SB(0, 1), b2 + hstep, voffB); PG8_STAGE(PG8_SA(0, 0), a2, voffA);
;             PG8_WAIT_V(8); PG8_WAIT_L(0); PG8_BAR; PG8_MMA(1, 0, At, B0); PG8_MMA(1, 1, At, B1); PG8_BAR; PG8_SCHED;
.LBB0_200:
	ds_read_b128 v[148:151], v154
	ds_read_b128 v[158:161], v154 offset:1024
	ds_read_b128 v[162:165], v154 offset:2048
	ds_read_b128 v[166:169], v154 offset:3072
	ds_read_b128 v[170:173], v155
	ds_read_b128 v[174:177], v155 offset:1024
	ds_read_b128 v[180:183], v155 offset:2048
	ds_read_b128 v[184:187], v155 offset:3072
	s_add_u32 s46, s44, 0x4000
	s_addc_u32 s47, s45, 0
	s_cmpk_eq_i32 s76, 0xa8
	s_cselect_b32 s50, s6, s46
	s_cselect_b32 s51, s7, s47
	s_cselect_b32 s48, s24, s74
	s_cselect_b32 s49, s25, s75
	s_add_u32 s46, s50, 0x8000
	s_addc_u32 s47, s51, 0
	s_sub_u32 s46, s44, 0x4000
	s_subb_u32 s47, s45, 0
	s_mov_b32 m0, s57
	s_nop 0
	global_load_lds_dwordx4 v130, s[46:47]
	s_mov_b32 m0, s58
	s_nop 0
	global_load_lds_dwordx4 v134, s[46:47]
	s_add_i32 m0, s26, 0xc000
	ds_read_b128 v[188:191], v156
	ds_read_b128 v[196:199], v156 offset:1024
	ds_read_b128 v[200:203], v156 offset:2048
	ds_read_b128 v[204:207], v156 offset:3072
	ds_read_b128 v[208:211], v156 offset:4096
	ds_read_b128 v[212:215], v156 offset:5120
	ds_read_b128 v[216:219], v156 offset:6144
	ds_read_b128 v[220:223], v156 offset:7168
	global_load_lds_dwordx4 v140, s[44:45]
	s_add_i32 m0, s26, 0xe000
	s_nop 0
	global_load_lds_dwordx4 v142, s[44:45]
	s_waitcnt vmcnt(8)
	s_waitcnt lgkmcnt(0)
	s_barrier
	s_setprio 1
	s_waitcnt lgkmcnt(0)
	v_mfma_f32_16x16x32_bf16 v[126:129], v[148:151], v[188:191], v[126:129]
	v_mfma_f32_16x16x32_bf16 v[126:129], v[158:161], v[196:199], v[126:129]
	v_mfma_f32_16x16x32_bf16 v[110:113], v[148:151], v[200:203], v[110:113]
	v_mfma_f32_16x16x32_bf16 v[110:113], v[158:161], v[204:207], v[110:113]
	v_mfma_f32_16x16x32_bf16 v[94:97], v[148:151], v[208:211], v[94:97]
	v_mfma_f32_16x16x32_bf16 v[94:97], v[158:161], v[212:215], v[94:97]
	v_mfma_f32_16x16x32_bf16 v[78:81], v[148:151], v[216:219], v[78:81]
	v_mfma_f32_16x16x32_bf16 v[78:81], v[158:161], v[220:223], v[78:81]
	v_mfma_f32_16x16x32_bf16 v[122:125], v[162:165], v[188:191], v[122:125]
	v_mfma_f32_16x16x32_bf16 v[122:125], v[166:169], v[196:199], v[122:125]
	v_mfma_f32_16x16x32_bf16 v[106:109], v[162:165], v[200:203], v[106:109]
	v_mfma_f32_16x16x32_bf16 v[106:109], v[166:169], v[204:207], v[106:109]
	v_mfma_f32_16x16x32_bf16 v[90:93], v[162:165], v[208:211], v[90:93]
	v_mfma_f32_16x16x32_bf16 v[90:93], v[166:169], v[212:215], v[90:93]
	v_mfma_f32_16x16x32_bf16 v[74:77], v[162:165], v[216:219], v[74:77]
	v_mfma_f32_16x16x32_bf16 v[74:77], v[166:169], v[220:223], v[74:77]
	s_setprio 0
	s_setprio 1
	v_mfma_f32_16x16x32_bf16 v[118:121], v[170:173], v[188:191], v[118:121]
	v_mfma_f32_16x16x32_bf16 v[118:121], v[174:177], v[196:199], v[118:121]
	v_mfma_f32_16x16x32_bf16 v[102:105], v[170:173], v[200:203], v[102:105]
	v_mfma_f32_16x16x32_bf16 v[102:105], v[174:177], v[204:207], v[102:105]
	v_mfma_f32_16x16x32_bf16 v[86:89], v[170:173], v[208:211], v[86:89]
	v_mfma_f32_16x16x32_bf16 v[86:89], v[174:177], v[212:215], v[86:89]
	v_mfma_f32_16x16x32_bf16 v[70:73], v[170:173], v[216:219], v[70:73]
	v_mfma_f32_16x16x32_bf16 v[70:73], v[174:177], v[220:223], v[70:73]
	v_mfma_f32_16x16x32_bf16 v[114:117], v[180:183], v[188:191], v[114:117]
	v_mfma_f32_16x16x32_bf16 v[114:117], v[184:187], v[196:199], v[114:117]
	v_mfma_f32_16x16x32_bf16 v[98:101], v[180:183], v[200:203], v[98:101]
	v_mfma_f32_16x16x32_bf16 v[98:101], v[184:187], v[204:207], v[98:101]
	v_mfma_f32_16x16x32_bf16 v[82:85], v[180:183], v[208:211], v[82:85]
	v_mfma_f32_16x16x32_bf16 v[82:85], v[184:187], v[212:215], v[82:85]
	v_mfma_f32_16x16x32_bf16 v[66:69], v[180:183], v[216:219], v[66:69]
	v_mfma_f32_16x16x32_bf16 v[66:69], v[184:187], v[220:223], v[66:69]
	s_setprio 0
	s_barrier
	s_add_i32 s77, s59, s3
	s_mov_b32 m0, s77
	ds_read_b128 v[188:191], v156 offset:16384
	ds_read_b128 v[196:199], v156 offset:17408
	ds_read_b128 v[200:203], v156 offset:18432
	ds_read_b128 v[204:207], v156 offset:19456
	ds_read_b128 v[208:211], v156 offset:20480
	ds_read_b128 v[212:215], v156 offset:21504
	ds_read_b128 v[216:219], v156 offset:22528
	ds_read_b128 v[220:223], v156 offset:23552
	global_load_lds_dwordx4 v132, s[48:49]
	s_add_i32 m0, s77, 0x2000
	s_add_u32 s78, s48, 0x4000
	v_lshl_add_u64 v[224:225], s[48:49], 0, v[136:137]
	s_addc_u32 s79, s49, 0
	s_add_i32 s77, s61, s3
	global_load_lds_dwordx4 v[224:225], off
	s_mov_b32 m0, s77
	s_nop 0
	global_load_lds_dwordx4 v132, s[78:79]
	s_add_i32 m0, s77, 0x2000
	s_nop 0
	global_load_lds_dwordx4 v136, s[78:79]
	s_waitcnt vmcnt(6)
	s_waitcnt lgkmcnt(0)
	s_barrier
	s_setprio 1
	s_waitcnt lgkmcnt(0)
	v_mfma_f32_16x16x32_bf16 v[62:65], v[148:151], v[188:191], v[62:65]
	v_mfma_f32_16x16x32_bf16 v[62:65], v[158:161], v[196:199], v[62:65]
	v_mfma_f32_16x16x32_bf16 v[46:49], v[148:151], v[200:203], v[46:49]
	v_mfma_f32_16x16x32_bf16 v[46:49], v[158:161], v[204:207], v[46:49]
	v_mfma_f32_16x16x32_bf16 v[30:33], v[148:151], v[208:211], v[30:33]
	v_mfma_f32_16x16x32_bf16 v[30:33], v[158:161], v[212:215], v[30:33]
	v_mfma_f32_16x16x32_bf16 v[14:17], v[148:151], v[216:219], v[14:17]
	v_mfma_f32_16x16x32_bf16 v[14:17], v[158:161], v[220:223], v[14:17]
	v_mfma_f32_16x16x32_bf16 v[58:61], v[162:165], v[188:191], v[58:61]
	v_mfma_f32_16x16x32_bf16 v[58:61], v[166:169], v[196:199], v[58:61]
	v_mfma_f32_16x16x32_bf16 v[42:45], v[162:165], v[200:203], v[42:45]
	v_mfma_f32_16x16x32_bf16 v[42:45], v[166:169], v[204:207], v[42:45]
	v_mfma_f32_16x16x32_bf16 v[26:29], v[162:165], v[208:211], v[26:29]
	v_mfma_f32_16x16x32_bf16 v[26:29], v[166:169], v[212:215], v[26:29]
	v_mfma_f32_16x16x32_bf16 v[10:13], v[162:165], v[216:219], v[10:13]
	v_mfma_f32_16x16x32_bf16 v[10:13], v[166:169], v[220:223], v[10:13]
	s_setprio 0
	s_setprio 1
	v_mfma_f32_16x16x32_bf16 v[54:57], v[170:173], v[188:191], v[54:57]
	v_mfma_f32_16x16x32_bf16 v[54:57], v[174:177], v[196:199], v[54:57]
	v_mfma_f32_16x16x32_bf16 v[38:41], v[170:173], v[200:203], v[38:41]
	v_mfma_f32_16x16x32_bf16 v[38:41], v[174:177], v[204:207], v[38:41]
	v_mfma_f32_16x16x32_bf16 v[22:25], v[170:173], v[208:211], v[22:25]
	v_mfma_f32_16x16x32_bf16 v[22:25], v[174:177], v[212:215], v[22:25]
	v_mfma_f32_16x16x32_bf16 v[6:9], v[170:173], v[216:219], v[6:9]
	v_mfma_f32_16x16x32_bf16 v[6:9], v[174:177], v[220:223], v[6:9]
	v_mfma_f32_16x16x32_bf16 v[50:53], v[180:183], v[188:191], v[50:53]
	v_mfma_f32_16x16x32_bf16 v[50:53], v[184:187], v[196:199], v[50:53]
	v_mfma_f32_16x16x32_bf16 v[34:37], v[180:183], v[200:203], v[34:37]
	v_mfma_f32_16x16x32_bf16 v[34:37], v[184:187], v[204:207], v[34:37]
	v_mfma_f32_16x16x32_bf16 v[18:21], v[180:183], v[208:211], v[18:21]
	v_mfma_f32_16x16x32_bf16 v[18:21], v[184:187], v[212:215], v[18:21]
	v_mfma_f32_16x16x32_bf16 v[2:5], v[180:183], v[216:219], v[2:5]
	v_mfma_f32_16x16x32_bf16 v[2:5], v[184:187], v[220:223], v[2:5]
	s_setprio 0
	s_barrier
; #define PG8_STAGE(bufoff, gbase, voff) do { _Pragma("unroll") for (int _i = 0; _i < 2; ++_i) \
;         __builtin_amdgcn_global_load_lds((const unsigned*)((const char*)(gbase) + (voff)[_i]), (PG8_LAS unsigned*)(lds + (bufoff) + ldsw + _i * 8192), 16, 0, 0); } while (0)
; #define PG8_LDA(dst, b, h) do { _Pragma("unroll") for (int m = 0; m < 4; ++m) _Pragma("unroll") for (int k = 0; k < 2; ++k) dst[m][k] = *(const PG8_LAS bf16x8*)(lds + PG8_SA(b, h) + aoff + m * 2048 + k * 1024); } while (0)
; #define PG8_LDB(dst, b, h) do { _Pragma("unroll") for (int n = 0; n < 2; ++n) _Pragma("unroll") for (int k = 0; k < 2; ++k) dst[n][k] = *(const PG8_LAS bf16x8*)(lds + PG8_SB(b, h) + boff + n * 2048 + k * 1024); } while (0)
; #define PG8_MMA(ai, bj, At, Bt) do { __builtin_amdgcn_s_setprio(1); _Pragma("unroll") for (int m = 0; m < 4; ++m) _Pragma("unroll") for (int n = 0; n < 2; ++n) _Pragma("unroll") for (int k = 0; k < 2; ++k) \
;         acc[ai][bj][m][n] = __builtin_amdgcn_mfma_f32_16x16x32_bf16(Bt[n][k], At[m][k], acc[ai][bj][m][n], 0, 0, 0); __builtin_amdgcn_s_setprio(0); } while (0)
; #define PG8_WAIT_V(n) asm volatile("s_waitcnt vmcnt(" #n ")" ::: "memory")
; #define PG8_WAIT_L(n) asm volatile("s_waitcnt lgkmcnt(" #n ")" ::: "memory")
; #define PG8_BAR __builtin_amdgcn_s_barrier()
; #define PG8_SCHED __builtin_amdgcn_sched_barrier(0)
; template <class Epi, class Sched, bool ALIGN_EPI = false, bool SP2 = false>
; __device__ __forceinline__ void gemm_phase(PG8_LAS unsigned char* lds, const Gemm g, const Sched& S, const Epi& E) {
;     ...
;             PG8_LDB(B0, 1, 0); PG8_LDB(B1, 1, 1); PG8_SCHED; PG8_LDA(At, 1, 0); PG8_STAGE(PG8_SA(0, 1), a2 + hstep, voffA);
;             PG8_WAIT_V(8); PG8_WAIT_L(0); PG8_BAR; PG8_MMA(0, 0, At, B0); PG8_MMA(0, 1, At, B1); PG8_BAR; PG8_SCHED;
;             PG8_LDA(At, 1, 1); PG8_STAGE(PG8_SB(1, 0), b3, voffB); PG8_STAGE(PG8_SB(1, 1), b3 + hstep, voffB); PG8_STAGE(PG8_SA(1, 0), a3, voffA);
;             PG8_WAIT_V(8); PG8_WAIT_L(0); PG8_BAR; PG8_MMA(1, 0, At, B0); PG8_MMA(1, 1, At, B1); PG8_BAR; PG8_SCHED;
	s_add_i32 s77, 0, 0x18000
	v_add_u32_e32 v138, s77, v153
	s_add_i32 s78, 0, 0x1c000
	ds_read_b128 v[148:151], v138
	ds_read_b128 v[158:161], v138 offset:1024
	ds_read_b128 v[162:165], v138 offset:2048
	ds_read_b128 v[166:169], v138 offset:3072
	v_add_u32_e32 v138, s78, v153
	ds_read_b128 v[170:173], v138
	ds_read_b128 v[174:177], v138 offset:1024
	ds_read_b128 v[180:183], v138 offset:2048
	ds_read_b128 v[184:187], v138 offset:3072
	s_mov_b32 m0, s26
	s_nop 0
	global_load_lds_dwordx4 v130, s[50:51]
	s_mov_b32 m0, s27
	s_nop 0
	global_load_lds_dwordx4 v134, s[50:51]
	s_add_u32 s50, s50, 0x4000
	s_addc_u32 s51, s51, 0
	s_mov_b32 m0, s28
	ds_read_b128 v[188:191], v156 offset:32768
	ds_read_b128 v[196:199], v156 offset:33792
	ds_read_b128 v[200:203], v156 offset:34816
	ds_read_b128 v[204:207], v156 offset:35840
	ds_read_b128 v[208:211], v156 offset:36864
	ds_read_b128 v[212:215], v156 offset:37888
	ds_read_b128 v[216:219], v156 offset:38912
	ds_read_b128 v[220:223], v156 offset:39936
	global_load_lds_dwordx4 v130, s[50:51]
	s_mov_b32 m0, s29
	s_nop 0
	global_load_lds_dwordx4 v134, s[50:51]
	s_waitcnt vmcnt(8)
	s_waitcnt lgkmcnt(0)
	s_barrier
	s_setprio 1
	s_waitcnt lgkmcnt(0)
	v_mfma_f32_16x16x32_bf16 v[126:129], v[148:151], v[188:191], v[126:129]
	v_mfma_f32_16x16x32_bf16 v[126:129], v[158:161], v[196:199], v[126:129]
	v_mfma_f32_16x16x32_bf16 v[110:113], v[148:151], v[200:203], v[110:113]
	v_mfma_f32_16x16x32_bf16 v[110:113], v[158:161], v[204:207], v[110:113]
	v_mfma_f32_16x16x32_bf16 v[94:97], v[148:151], v[208:211], v[94:97]
	v_mfma_f32_16x16x32_bf16 v[94:97], v[158:161], v[212:215], v[94:97]
	v_mfma_f32_16x16x32_bf16 v[78:81], v[148:151], v[216:219], v[78:81]
	v_mfma_f32_16x16x32_bf16 v[78:81], v[158:161], v[220:223], v[78:81]
	v_mfma_f32_16x16x32_bf16 v[122:125], v[162:165], v[188:191], v[122:125]
	v_mfma_f32_16x16x32_bf16 v[122:125], v[166:169], v[196:199], v[122:125]
	v_mfma_f32_16x16x32_bf16 v[106:109], v[162:165], v[200:203], v[106:109]
	v_mfma_f32_16x16x32_bf16 v[106:109], v[166:169], v[204:207], v[106:109]
	v_mfma_f32_16x16x32_bf16 v[90:93], v[162:165], v[208:211], v[90:93]
	v_mfma_f32_16x16x32_bf16 v[90:93], v[166:169], v[212:215], v[90:93]
	v_mfma_f32_16x16x32_bf16 v[74:77], v[162:165], v[216:219], v[74:77]
	v_mfma_f32_16x16x32_bf16 v[74:77], v[166:169], v[220:223], v[74:77]
	s_setprio 0
	s_setprio 1
	v_mfma_f32_16x16x32_bf16 v[118:121], v[170:173], v[188:191], v[118:121]
	v_mfma_f32_16x16x32_bf16 v[118:121], v[174:177], v[196:199], v[118:121]
	v_mfma_f32_16x16x32_bf16 v[102:105], v[170:173], v[200:203], v[102:105]
	v_mfma_f32_16x16x32_bf16 v[102:105], v[174:177], v[204:207], v[102:105]
	v_mfma_f32_16x16x32_bf16 v[86:89], v[170:173], v[208:211], v[86:89]
	v_mfma_f32_16x16x32_bf16 v[86:89], v[174:177], v[212:215], v[86:89]
	v_mfma_f32_16x16x32_bf16 v[70:73], v[170:173], v[216:219], v[70:73]
	v_mfma_f32_16x16x32_bf16 v[70:73], v[174:177], v[220:223], v[70:73]
	v_mfma_f32_16x16x32_bf16 v[114:117], v[180:183], v[188:191], v[114:117]
	v_mfma_f32_16x16x32_bf16 v[114:117], v[184:187], v[196:199], v[114:117]
	v_mfma_f32_16x16x32_bf16 v[98:101], v[180:183], v[200:203], v[98:101]
	v_mfma_f32_16x16x32_bf16 v[98:101], v[184:187], v[204:207], v[98:101]
	v_mfma_f32_16x16x32_bf16 v[82:85], v[180:183], v[208:211], v[82:85]
	v_mfma_f32_16x16x32_bf16 v[82:85], v[184:187], v[212:215], v[82:85]
	v_mfma_f32_16x16x32_bf16 v[66:69], v[180:183], v[216:219], v[66:69]
	v_mfma_f32_16x16x32_bf16 v[66:69], v[184:187], v[220:223], v[66:69]
	s_setprio 0
	s_barrier
	s_add_u32 s50, s48, 0x8000
	s_addc_u32 s51, s49, 0
	s_add_i32 s77, s77, s3
	s_mov_b32 m0, s77
	ds_read_b128 v[188:191], v156 offset:49152
	ds_read_b128 v[196:199], v156 offset:50176
	ds_read_b128 v[200:203], v156 offset:51200
	ds_read_b128 v[204:207], v156 offset:52224
	ds_read_b128 v[208:211], v156 offset:53248
	ds_read_b128 v[212:215], v156 offset:54272
	ds_read_b128 v[216:219], v156 offset:55296
	ds_read_b128 v[220:223], v156 offset:56320
	global_load_lds_dwordx4 v132, s[50:51]
	s_add_i32 m0, s77, 0x2000
	s_add_u32 s48, s48, 0xc000
	v_lshl_add_u64 v[224:225], s[50:51], 0, v[136:137]
	s_addc_u32 s49, s49, 0
	s_add_i32 s50, s78, s3
	global_load_lds_dwordx4 v[224:225], off
	s_mov_b32 m0, s50
	s_nop 0
	global_load_lds_dwordx4 v132, s[48:49]
	s_add_i32 m0, s50, 0x2000
	s_nop 0
	global_load_lds_dwordx4 v136, s[48:49]
	s_waitcnt vmcnt(6)
	s_waitcnt lgkmcnt(0)
	s_barrier
	s_setprio 1
	s_waitcnt lgkmcnt(0)
	v_mfma_f32_16x16x32_bf16 v[62:65], v[148:151], v[188:191], v[62:65]
	v_mfma_f32_16x16x32_bf16 v[62:65], v[158:161], v[196:199], v[62:65]
	v_mfma_f32_16x16x32_bf16 v[46:49], v[148:151], v[200:203], v[46:49]
	v_mfma_f32_16x16x32_bf16 v[46:49], v[158:161], v[204:207], v[46:49]
	v_mfma_f32_16x16x32_bf16 v[30:33], v[148:151], v[208:211], v[30:33]
	v_mfma_f32_16x16x32_bf16 v[30:33], v[158:161], v[212:215], v[30:33]
	v_mfma_f32_16x16x32_bf16 v[14:17], v[148:151], v[216:219], v[14:17]
	v_mfma_f32_16x16x32_bf16 v[14:17], v[158:161], v[220:223], v[14:17]
	v_mfma_f32_16x16x32_bf16 v[58:61], v[162:165], v[188:191], v[58:61]
	v_mfma_f32_16x16x32_bf16 v[58:61], v[166:169], v[196:199], v[58:61]
	v_mfma_f32_16x16x32_bf16 v[42:45], v[162:165], v[200:203], v[42:45]
	v_mfma_f32_16x16x32_bf16 v[42:45], v[166:169], v[204:207], v[42:45]
	v_mfma_f32_16x16x32_bf16 v[26:29], v[162:165], v[208:211], v[26:29]
	v_mfma_f32_16x16x32_bf16 v[26:29], v[166:169], v[212:215], v[26:29]
	v_mfma_f32_16x16x32_bf16 v[10:13], v[162:165], v[216:219], v[10:13]
	v_mfma_f32_16x16x32_bf16 v[10:13], v[166:169], v[220:223], v[10:13]
	s_setprio 0
	s_setprio 1
	v_mfma_f32_16x16x32_bf16 v[54:57], v[170:173], v[188:191], v[54:57]
	v_mfma_f32_16x16x32_bf16 v[54:57], v[174:177], v[196:199], v[54:57]
	v_mfma_f32_16x16x32_bf16 v[38:41], v[170:173], v[200:203], v[38:41]
	v_mfma_f32_16x16x32_bf16 v[38:41], v[174:177], v[204:207], v[38:41]
	v_mfma_f32_16x16x32_bf16 v[22:25], v[170:173], v[208:211], v[22:25]
	v_mfma_f32_16x16x32_bf16 v[22:25], v[174:177], v[212:215], v[22:25]
	v_mfma_f32_16x16x32_bf16 v[6:9], v[170:173], v[216:219], v[6:9]
	v_mfma_f32_16x16x32_bf16 v[6:9], v[174:177], v[220:223], v[6:9]
	v_mfma_f32_16x16x32_bf16 v[50:53], v[180:183], v[188:191], v[50:53]
	v_mfma_f32_16x16x32_bf16 v[50:53], v[184:187], v[196:199], v[50:53]
	v_mfma_f32_16x16x32_bf16 v[34:37], v[180:183], v[200:203], v[34:37]
	v_mfma_f32_16x16x32_bf16 v[34:37], v[184:187], v[204:207], v[34:37]
	v_mfma_f32_16x16x32_bf16 v[18:21], v[180:183], v[208:211], v[18:21]
	v_mfma_f32_16x16x32_bf16 v[18:21], v[184:187], v[212:215], v[18:21]
	v_mfma_f32_16x16x32_bf16 v[2:5], v[180:183], v[216:219], v[2:5]
	v_mfma_f32_16x16x32_bf16 v[2:5], v[184:187], v[220:223], v[2:5]
	s_setprio 0
	s_barrier
	s_add_i32 s76, s76, 2
	s_add_u32 s44, s44, 0x10000
	s_addc_u32 s45, s45, 0
	s_add_u32 s74, s74, 0x10000
	s_addc_u32 s75, s75, 0
	s_cmpk_gt_u32 s76, 0xa9
	s_cbranch_scc0 .LBB0_200
	s_and_b64 vcc, exec, s[18:19]
	s_cbranch_vccz .LBB0_203
	s_barrier

; #define PG8_STAGE(bufoff, gbase, voff) do { _Pragma("unroll") for (int _i = 0; _i < 2; ++_i) \
;         __builtin_amdgcn_global_load_lds((const unsigned*)((const char*)(gbase) + (voff)[_i]), (PG8_LAS unsigned*)(lds + (bufoff) + ldsw + _i * 8192), 16, 0, 0); } while (0)
; #define PG8_LDA(dst, b, h) do { _Pragma("unroll") for (int m = 0; m < 4; ++m) _Pragma("unroll") for (int k = 0; k < 2; ++k) dst[m][k] = *(const PG8_LAS bf16x8*)(lds + PG8_SA(b, h) + aoff + m * 2048 + k * 1024); } while (0)
; #define PG8_LDB(dst, b, h) do { _Pragma("unroll") for (int n = 0; n < 2; ++n) _Pragma("unroll") for (int k = 0; k < 2; ++k) dst[n][k] = *(const PG8_LAS bf16x8*)(lds + PG8_SB(b, h) + boff + n * 2048 + k * 1024); } while (0)
; #define PG8_MMA(ai, bj, At, Bt) do { __builtin_amdgcn_s_setprio(1); _Pragma("unroll") for (int m = 0; m < 4; ++m) _Pragma("unroll") for (int n = 0; n < 2; ++n) _Pragma("unroll") for (int k = 0; k < 2; ++k) \
;         acc[ai][bj][m][n] = __builtin_amdgcn_mfma_f32_16x16x32_bf16(Bt[n][k], At[m][k], acc[ai][bj][m][n], 0, 0, 0); __builtin_amdgcn_s_setprio(0); } while (0)
; #define PG8_WAIT_V(n) asm volatile("s_waitcnt vmcnt(" #n ")" ::: "memory")
; #define PG8_WAIT_L(n) asm volatile("s_waitcnt lgkmcnt(" #n ")" ::: "memory")
; template <class Epi, class Sched, bool ALIGN_EPI = false, bool SP2 = false>
; __device__ __forceinline__ void gemm_phase(PG8_LAS unsigned char* lds, const Gemm g, const Sched& S, const Epi& E) {
;     ...
;             const bool last = (t == nt - 2);
;             const char* a1 = cA + (size_t)(t + 1) * kstep;
;             const char* a2 = last ? nA : cA + (size_t)(t + 2) * kstep; const char* b2 = last ? nB : cB + (size_t)(t + 2) * kstep;
;             const char* a3 = a2 + kstep; const char* b3 = b2 + kstep;
;             if (last && has_next) S.a_ready(nxt);
;             if constexpr (SP2) {
;             PG8_LDB(B0, 0, 0); PG8_LDB(B1, 0, 1); PG8_SCHED; PG8_LDA(At, 0, 0); PG8_STAGE(PG8_SA(1, 1), a1 + hstep, voffA);
;             PG8_WAIT_V(8); PG8_WAIT_L(0); PG8_BAR; PG8_MMA(0, 0, At, B0); PG8_MMA(0, 1, At, B1); PG8_BAR; PG8_SCHED;
;             PG8_LDA(At, 0, 1); PG8_STAGE(PG8_SB(0, 0), b2, voffB); PG8_STAGE(PG8_SB(0, 1), b2 + hstep, voffB); PG8_STAGE(PG8_SA(0, 0), a2, voffA);
;             PG8_WAIT_V(8); PG8_WAIT_L(0); PG8_BAR; PG8_MMA(1, 0, At, B0); PG8_MMA(1, 1, At, B1); PG8_BAR; PG8_SCHED;
.LBB0_290:
	ds_read_b128 v[146:149], v162
	ds_read_b128 v[150:153], v162 offset:1024
	ds_read_b128 v[154:157], v162 offset:2048
	ds_read_b128 v[168:171], v162 offset:3072
	ds_read_b128 v[172:175], v163
	ds_read_b128 v[180:183], v163 offset:1024
	ds_read_b128 v[184:187], v163 offset:2048
	ds_read_b128 v[188:191], v163 offset:3072
	s_add_u32 s59, s72, 0x4000
	s_addc_u32 s62, s73, 0
	s_cmp_eq_u32 s58, 60
	s_cselect_b32 s78, s19, s59
	s_cselect_b32 s79, s5, s62
	s_cselect_b32 s76, s26, s33
	s_cselect_b32 s77, s17, s56
	s_add_u32 s74, s78, 0x8000
	s_addc_u32 s75, s79, 0
	s_sub_u32 s74, s72, 0x4000
	s_subb_u32 s75, s73, 0
	s_mov_b32 m0, s51
	s_nop 0
	global_load_lds_dwordx4 v130, s[74:75]
	s_mov_b32 m0, s57
	s_nop 0
	global_load_lds_dwordx4 v134, s[74:75]
	s_add_i32 m0, s15, 0xc000
	ds_read_b128 v[198:201], v164
	ds_read_b128 v[202:205], v164 offset:1024
	ds_read_b128 v[206:209], v164 offset:2048
	ds_read_b128 v[210:213], v164 offset:3072
	ds_read_b128 v[214:217], v164 offset:4096
	ds_read_b128 v[218:221], v164 offset:5120
	ds_read_b128 v[222:225], v164 offset:6144
	ds_read_b128 v[226:229], v164 offset:7168
	global_load_lds_dwordx4 v138, s[72:73]
	s_add_i32 m0, s15, 0xe000
	s_nop 0
	global_load_lds_dwordx4 v140, s[72:73]
	s_waitcnt vmcnt(8)
	s_waitcnt lgkmcnt(0)
	s_barrier
	s_setprio 1
	s_waitcnt lgkmcnt(0)
	v_mfma_f32_16x16x32_bf16 v[126:129], v[146:149], v[198:201], v[126:129]
	v_mfma_f32_16x16x32_bf16 v[126:129], v[150:153], v[202:205], v[126:129]
	v_mfma_f32_16x16x32_bf16 v[110:113], v[146:149], v[206:209], v[110:113]
	v_mfma_f32_16x16x32_bf16 v[110:113], v[150:153], v[210:213], v[110:113]
	v_mfma_f32_16x16x32_bf16 v[94:97], v[146:149], v[214:217], v[94:97]
	v_mfma_f32_16x16x32_bf16 v[94:97], v[150:153], v[218:221], v[94:97]
	v_mfma_f32_16x16x32_bf16 v[78:81], v[146:149], v[222:225], v[78:81]
	v_mfma_f32_16x16x32_bf16 v[78:81], v[150:153], v[226:229], v[78:81]
	v_mfma_f32_16x16x32_bf16 v[122:125], v[154:157], v[198:201], v[122:125]
	v_mfma_f32_16x16x32_bf16 v[122:125], v[168:171], v[202:205], v[122:125]
	v_mfma_f32_16x16x32_bf16 v[106:109], v[154:157], v[206:209], v[106:109]
	v_mfma_f32_16x16x32_bf16 v[106:109], v[168:171], v[210:213], v[106:109]
	v_mfma_f32_16x16x32_bf16 v[90:93], v[154:157], v[214:217], v[90:93]
	v_mfma_f32_16x16x32_bf16 v[90:93], v[168:171], v[218:221], v[90:93]
	v_mfma_f32_16x16x32_bf16 v[74:77], v[154:157], v[222:225], v[74:77]
	v_mfma_f32_16x16x32_bf16 v[74:77], v[168:171], v[226:229], v[74:77]
	s_setprio 0
	s_setprio 1
	v_mfma_f32_16x16x32_bf16 v[118:121], v[172:175], v[198:201], v[118:121]
	v_mfma_f32_16x16x32_bf16 v[118:121], v[180:183], v[202:205], v[118:121]
	v_mfma_f32_16x16x32_bf16 v[102:105], v[172:175], v[206:209], v[102:105]
	v_mfma_f32_16x16x32_bf16 v[102:105], v[180:183], v[210:213], v[102:105]
	v_mfma_f32_16x16x32_bf16 v[86:89], v[172:175], v[214:217], v[86:89]
	v_mfma_f32_16x16x32_bf16 v[86:89], v[180:183], v[218:221], v[86:89]
	v_mfma_f32_16x16x32_bf16 v[70:73], v[172:175], v[222:225], v[70:73]
	v_mfma_f32_16x16x32_bf16 v[70:73], v[180:183], v[226:229], v[70:73]
	v_mfma_f32_16x16x32_bf16 v[114:117], v[184:187], v[198:201], v[114:117]
	v_mfma_f32_16x16x32_bf16 v[114:117], v[188:191], v[202:205], v[114:117]
	v_mfma_f32_16x16x32_bf16 v[98:101], v[184:187], v[206:209], v[98:101]
	v_mfma_f32_16x16x32_bf16 v[98:101], v[188:191], v[210:213], v[98:101]
	v_mfma_f32_16x16x32_bf16 v[82:85], v[184:187], v[214:217], v[82:85]
	v_mfma_f32_16x16x32_bf16 v[82:85], v[188:191], v[218:221], v[82:85]
	v_mfma_f32_16x16x32_bf16 v[66:69], v[184:187], v[222:225], v[66:69]
	v_mfma_f32_16x16x32_bf16 v[66:69], v[188:191], v[226:229], v[66:69]
	s_setprio 0
	s_barrier
	s_add_i32 s59, s81, s3
	s_mov_b32 m0, s59
	ds_read_b128 v[198:201], v164 offset:16384
	ds_read_b128 v[202:205], v164 offset:17408
	ds_read_b128 v[206:209], v164 offset:18432
	ds_read_b128 v[210:213], v164 offset:19456
	ds_read_b128 v[214:217], v164 offset:20480
	ds_read_b128 v[218:221], v164 offset:21504
	ds_read_b128 v[222:225], v164 offset:22528
	ds_read_b128 v[226:229], v164 offset:23552
	global_load_lds_dwordx4 v132, s[76:77]
	s_add_i32 m0, s59, 0x2000
	s_add_u32 s62, s76, 0x4000
	v_lshl_add_u64 v[158:159], s[76:77], 0, v[136:137]
	s_addc_u32 s63, s77, 0
	s_add_i32 s59, s82, s3
	global_load_lds_dwordx4 v[158:159], off
	s_mov_b32 m0, s59
	s_nop 0
	global_load_lds_dwordx4 v132, s[62:63]
	s_add_i32 m0, s59, 0x2000
	s_nop 0
	global_load_lds_dwordx4 v136, s[62:63]
	s_waitcnt vmcnt(6)
	s_waitcnt lgkmcnt(0)
	s_barrier
	s_setprio 1
	s_waitcnt lgkmcnt(0)
	v_mfma_f32_16x16x32_bf16 v[62:65], v[146:149], v[198:201], v[62:65]
	v_mfma_f32_16x16x32_bf16 v[62:65], v[150:153], v[202:205], v[62:65]
	v_mfma_f32_16x16x32_bf16 v[46:49], v[146:149], v[206:209], v[46:49]
	v_mfma_f32_16x16x32_bf16 v[46:49], v[150:153], v[210:213], v[46:49]
	v_mfma_f32_16x16x32_bf16 v[30:33], v[146:149], v[214:217], v[30:33]
	v_mfma_f32_16x16x32_bf16 v[30:33], v[150:153], v[218:221], v[30:33]
	v_mfma_f32_16x16x32_bf16 v[14:17], v[146:149], v[222:225], v[14:17]
	v_mfma_f32_16x16x32_bf16 v[14:17], v[150:153], v[226:229], v[14:17]
	v_mfma_f32_16x16x32_bf16 v[58:61], v[154:157], v[198:201], v[58:61]
	v_mfma_f32_16x16x32_bf16 v[58:61], v[168:171], v[202:205], v[58:61]
	v_mfma_f32_16x16x32_bf16 v[42:45], v[154:157], v[206:209], v[42:45]
	v_mfma_f32_16x16x32_bf16 v[42:45], v[168:171], v[210:213], v[42:45]
	v_mfma_f32_16x16x32_bf16 v[26:29], v[154:157], v[214:217], v[26:29]
	v_mfma_f32_16x16x32_bf16 v[26:29], v[168:171], v[218:221], v[26:29]
	v_mfma_f32_16x16x32_bf16 v[10:13], v[154:157], v[222:225], v[10:13]
	v_mfma_f32_16x16x32_bf16 v[10:13], v[168:171], v[226:229], v[10:13]
	s_setprio 0
	s_setprio 1
	v_mfma_f32_16x16x32_bf16 v[54:57], v[172:175], v[198:201], v[54:57]
	v_mfma_f32_16x16x32_bf16 v[54:57], v[180:183], v[202:205], v[54:57]
	v_mfma_f32_16x16x32_bf16 v[38:41], v[172:175], v[206:209], v[38:41]
	v_mfma_f32_16x16x32_bf16 v[38:41], v[180:183], v[210:213], v[38:41]
	v_mfma_f32_16x16x32_bf16 v[22:25], v[172:175], v[214:217], v[22:25]
	v_mfma_f32_16x16x32_bf16 v[22:25], v[180:183], v[218:221], v[22:25]
	v_mfma_f32_16x16x32_bf16 v[6:9], v[172:175], v[222:225], v[6:9]
	v_mfma_f32_16x16x32_bf16 v[6:9], v[180:183], v[226:229], v[6:9]
	v_mfma_f32_16x16x32_bf16 v[50:53], v[184:187], v[198:201], v[50:53]
	v_mfma_f32_16x16x32_bf16 v[50:53], v[188:191], v[202:205], v[50:53]
	v_mfma_f32_16x16x32_bf16 v[34:37], v[184:187], v[206:209], v[34:37]
	v_mfma_f32_16x16x32_bf16 v[34:37], v[188:191], v[210:213], v[34:37]
	v_mfma_f32_16x16x32_bf16 v[18:21], v[184:187], v[214:217], v[18:21]
	v_mfma_f32_16x16x32_bf16 v[18:21], v[188:191], v[218:221], v[18:21]
	v_mfma_f32_16x16x32_bf16 v[2:5], v[184:187], v[222:225], v[2:5]
	v_mfma_f32_16x16x32_bf16 v[2:5], v[188:191], v[226:229], v[2:5]
	s_setprio 0
	s_barrier
; #define PG8_STAGE(bufoff, gbase, voff) do { _Pragma("unroll") for (int _i = 0; _i < 2; ++_i) \
;         __builtin_amdgcn_global_load_lds((const unsigned*)((const char*)(gbase) + (voff)[_i]), (PG8_LAS unsigned*)(lds + (bufoff) + ldsw + _i * 8192), 16, 0, 0); } while (0)
; #define PG8_LDA(dst, b, h) do { _Pragma("unroll") for (int m = 0; m < 4; ++m) _Pragma("unroll") for (int k = 0; k < 2; ++k) dst[m][k] = *(const PG8_LAS bf16x8*)(lds + PG8_SA(b, h) + aoff + m * 2048 + k * 1024); } while (0)
; #define PG8_LDB(dst, b, h) do { _Pragma("unroll") for (int n = 0; n < 2; ++n) _Pragma("unroll") for (int k = 0; k < 2; ++k) dst[n][k] = *(const PG8_LAS bf16x8*)(lds + PG8_SB(b, h) + boff + n * 2048 + k * 1024); } while (0)
; #define PG8_MMA(ai, bj, At, Bt) do { __builtin_amdgcn_s_setprio(1); _Pragma("unroll") for (int m = 0; m < 4; ++m) _Pragma("unroll") for (int n = 0; n < 2; ++n) _Pragma("unroll") for (int k = 0; k < 2; ++k) \
;         acc[ai][bj][m][n] = __builtin_amdgcn_mfma_f32_16x16x32_bf16(Bt[n][k], At[m][k], acc[ai][bj][m][n], 0, 0, 0); __builtin_amdgcn_s_setprio(0); } while (0)
; #define PG8_WAIT_V(n) asm volatile("s_waitcnt vmcnt(" #n ")" ::: "memory")
; #define PG8_WAIT_L(n) asm volatile("s_waitcnt lgkmcnt(" #n ")" ::: "memory")
; #define PG8_BAR __builtin_amdgcn_s_barrier()
; #define PG8_SCHED __builtin_amdgcn_sched_barrier(0)
; template <class Epi, class Sched, bool ALIGN_EPI = false, bool SP2 = false>
; __device__ __forceinline__ void gemm_phase(PG8_LAS unsigned char* lds, const Gemm g, const Sched& S, const Epi& E) {
;     ...
;             PG8_LDB(B0, 1, 0); PG8_LDB(B1, 1, 1); PG8_SCHED; PG8_LDA(At, 1, 0); PG8_STAGE(PG8_SA(0, 1), a2 + hstep, voffA);
;             PG8_WAIT_V(8); PG8_WAIT_L(0); PG8_BAR; PG8_MMA(0, 0, At, B0); PG8_MMA(0, 1, At, B1); PG8_BAR; PG8_SCHED;
;             PG8_LDA(At, 1, 1); PG8_STAGE(PG8_SB(1, 0), b3, voffB); PG8_STAGE(PG8_SB(1, 1), b3 + hstep, voffB); PG8_STAGE(PG8_SA(1, 0), a3, voffA);
;             PG8_WAIT_V(8); PG8_WAIT_L(0); PG8_BAR; PG8_MMA(1, 0, At, B0); PG8_MMA(1, 1, At, B1); PG8_BAR; PG8_SCHED;
	s_add_i32 s59, 0, 0x18000
	v_add_u32_e32 v158, s59, v160
	s_add_i32 s64, 0, 0x1c000
	ds_read_b128 v[146:149], v158
	ds_read_b128 v[150:153], v158 offset:1024
	ds_read_b128 v[154:157], v158 offset:2048
	ds_read_b128 v[168:171], v158 offset:3072
	v_add_u32_e32 v158, s64, v160
	ds_read_b128 v[172:175], v158
	ds_read_b128 v[180:183], v158 offset:1024
	ds_read_b128 v[184:187], v158 offset:2048
	ds_read_b128 v[188:191], v158 offset:3072
	s_mov_b32 m0, s15
	s_nop 0
	global_load_lds_dwordx4 v130, s[78:79]
	s_mov_b32 m0, s27
	s_nop 0
	global_load_lds_dwordx4 v134, s[78:79]
	s_add_u32 s62, s78, 0x4000
	s_addc_u32 s63, s79, 0
	s_mov_b32 m0, s28
	ds_read_b128 v[198:201], v164 offset:32768
	ds_read_b128 v[202:205], v164 offset:33792
	ds_read_b128 v[206:209], v164 offset:34816
	ds_read_b128 v[210:213], v164 offset:35840
	ds_read_b128 v[214:217], v164 offset:36864
	ds_read_b128 v[218:221], v164 offset:37888
	ds_read_b128 v[222:225], v164 offset:38912
	ds_read_b128 v[226:229], v164 offset:39936
	global_load_lds_dwordx4 v130, s[62:63]
	s_mov_b32 m0, s29
	s_nop 0
	global_load_lds_dwordx4 v134, s[62:63]
	s_waitcnt vmcnt(8)
	s_waitcnt lgkmcnt(0)
	s_barrier
	s_setprio 1
	s_waitcnt lgkmcnt(0)
	v_mfma_f32_16x16x32_bf16 v[126:129], v[146:149], v[198:201], v[126:129]
	v_mfma_f32_16x16x32_bf16 v[126:129], v[150:153], v[202:205], v[126:129]
	v_mfma_f32_16x16x32_bf16 v[110:113], v[146:149], v[206:209], v[110:113]
	v_mfma_f32_16x16x32_bf16 v[110:113], v[150:153], v[210:213], v[110:113]
	v_mfma_f32_16x16x32_bf16 v[94:97], v[146:149], v[214:217], v[94:97]
	v_mfma_f32_16x16x32_bf16 v[94:97], v[150:153], v[218:221], v[94:97]
	v_mfma_f32_16x16x32_bf16 v[78:81], v[146:149], v[222:225], v[78:81]
	v_mfma_f32_16x16x32_bf16 v[78:81], v[150:153], v[226:229], v[78:81]
	v_mfma_f32_16x16x32_bf16 v[122:125], v[154:157], v[198:201], v[122:125]
	v_mfma_f32_16x16x32_bf16 v[122:125], v[168:171], v[202:205], v[122:125]
	v_mfma_f32_16x16x32_bf16 v[106:109], v[154:157], v[206:209], v[106:109]
	v_mfma_f32_16x16x32_bf16 v[106:109], v[168:171], v[210:213], v[106:109]
	v_mfma_f32_16x16x32_bf16 v[90:93], v[154:157], v[214:217], v[90:93]
	v_mfma_f32_16x16x32_bf16 v[90:93], v[168:171], v[218:221], v[90:93]
	v_mfma_f32_16x16x32_bf16 v[74:77], v[154:157], v[222:225], v[74:77]
	v_mfma_f32_16x16x32_bf16 v[74:77], v[168:171], v[226:229], v[74:77]
	s_setprio 0
	s_setprio 1
	v_mfma_f32_16x16x32_bf16 v[118:121], v[172:175], v[198:201], v[118:121]
	v_mfma_f32_16x16x32_bf16 v[118:121], v[180:183], v[202:205], v[118:121]
	v_mfma_f32_16x16x32_bf16 v[102:105], v[172:175], v[206:209], v[102:105]
	v_mfma_f32_16x16x32_bf16 v[102:105], v[180:183], v[210:213], v[102:105]
	v_mfma_f32_16x16x32_bf16 v[86:89], v[172:175], v[214:217], v[86:89]
	v_mfma_f32_16x16x32_bf16 v[86:89], v[180:183], v[218:221], v[86:89]
	v_mfma_f32_16x16x32_bf16 v[70:73], v[172:175], v[222:225], v[70:73]
	v_mfma_f32_16x16x32_bf16 v[70:73], v[180:183], v[226:229], v[70:73]
	v_mfma_f32_16x16x32_bf16 v[114:117], v[184:187], v[198:201], v[114:117]
	v_mfma_f32_16x16x32_bf16 v[114:117], v[188:191], v[202:205], v[114:117]
	v_mfma_f32_16x16x32_bf16 v[98:101], v[184:187], v[206:209], v[98:101]
	v_mfma_f32_16x16x32_bf16 v[98:101], v[188:191], v[210:213], v[98:101]
	v_mfma_f32_16x16x32_bf16 v[82:85], v[184:187], v[214:217], v[82:85]
	v_mfma_f32_16x16x32_bf16 v[82:85], v[188:191], v[218:221], v[82:85]
	v_mfma_f32_16x16x32_bf16 v[66:69], v[184:187], v[222:225], v[66:69]
	v_mfma_f32_16x16x32_bf16 v[66:69], v[188:191], v[226:229], v[66:69]
	s_setprio 0
	s_barrier
	s_add_u32 s62, s76, 0x8000
	s_addc_u32 s63, s77, 0
	s_add_i32 s59, s59, s3
	s_mov_b32 m0, s59
	ds_read_b128 v[198:201], v164 offset:49152
	ds_read_b128 v[202:205], v164 offset:50176
	ds_read_b128 v[206:209], v164 offset:51200
	ds_read_b128 v[210:213], v164 offset:52224
	ds_read_b128 v[214:217], v164 offset:53248
	ds_read_b128 v[218:221], v164 offset:54272
	ds_read_b128 v[222:225], v164 offset:55296
	ds_read_b128 v[226:229], v164 offset:56320
	global_load_lds_dwordx4 v132, s[62:63]
	s_add_i32 m0, s59, 0x2000
	v_lshl_add_u64 v[158:159], s[62:63], 0, v[136:137]
	s_add_u32 s62, s76, 0xc000
	s_addc_u32 s63, s77, 0
	s_add_i32 s59, s64, s3
	global_load_lds_dwordx4 v[158:159], off
	s_mov_b32 m0, s59
	s_nop 0
	global_load_lds_dwordx4 v132, s[62:63]
	s_add_i32 m0, s59, 0x2000
	s_nop 0
	global_load_lds_dwordx4 v136, s[62:63]
	s_waitcnt vmcnt(6)
	s_waitcnt lgkmcnt(0)
	s_barrier
	s_setprio 1
	s_waitcnt lgkmcnt(0)
	v_mfma_f32_16x16x32_bf16 v[62:65], v[146:149], v[198:201], v[62:65]
	v_mfma_f32_16x16x32_bf16 v[62:65], v[150:153], v[202:205], v[62:65]
	v_mfma_f32_16x16x32_bf16 v[46:49], v[146:149], v[206:209], v[46:49]
	v_mfma_f32_16x16x32_bf16 v[46:49], v[150:153], v[210:213], v[46:49]
	v_mfma_f32_16x16x32_bf16 v[30:33], v[146:149], v[214:217], v[30:33]
	v_mfma_f32_16x16x32_bf16 v[30:33], v[150:153], v[218:221], v[30:33]
	v_mfma_f32_16x16x32_bf16 v[14:17], v[146:149], v[222:225], v[14:17]
	v_mfma_f32_16x16x32_bf16 v[14:17], v[150:153], v[226:229], v[14:17]
	v_mfma_f32_16x16x32_bf16 v[58:61], v[154:157], v[198:201], v[58:61]
	v_mfma_f32_16x16x32_bf16 v[58:61], v[168:171], v[202:205], v[58:61]
	v_mfma_f32_16x16x32_bf16 v[42:45], v[154:157], v[206:209], v[42:45]
	v_mfma_f32_16x16x32_bf16 v[42:45], v[168:171], v[210:213], v[42:45]
	v_mfma_f32_16x16x32_bf16 v[26:29], v[154:157], v[214:217], v[26:29]
	v_mfma_f32_16x16x32_bf16 v[26:29], v[168:171], v[218:221], v[26:29]
	v_mfma_f32_16x16x32_bf16 v[10:13], v[154:157], v[222:225], v[10:13]
	v_mfma_f32_16x16x32_bf16 v[10:13], v[168:171], v[226:229], v[10:13]
	s_setprio 0
	s_setprio 1
	v_mfma_f32_16x16x32_bf16 v[54:57], v[172:175], v[198:201], v[54:57]
	v_mfma_f32_16x16x32_bf16 v[54:57], v[180:183], v[202:205], v[54:57]
	v_mfma_f32_16x16x32_bf16 v[38:41], v[172:175], v[206:209], v[38:41]
	v_mfma_f32_16x16x32_bf16 v[38:41], v[180:183], v[210:213], v[38:41]
	v_mfma_f32_16x16x32_bf16 v[22:25], v[172:175], v[214:217], v[22:25]
	v_mfma_f32_16x16x32_bf16 v[22:25], v[180:183], v[218:221], v[22:25]
	v_mfma_f32_16x16x32_bf16 v[6:9], v[172:175], v[222:225], v[6:9]
	v_mfma_f32_16x16x32_bf16 v[6:9], v[180:183], v[226:229], v[6:9]
	v_mfma_f32_16x16x32_bf16 v[50:53], v[184:187], v[198:201], v[50:53]
	v_mfma_f32_16x16x32_bf16 v[50:53], v[188:191], v[202:205], v[50:53]
	v_mfma_f32_16x16x32_bf16 v[34:37], v[184:187], v[206:209], v[34:37]
	v_mfma_f32_16x16x32_bf16 v[34:37], v[188:191], v[210:213], v[34:37]
	v_mfma_f32_16x16x32_bf16 v[18:21], v[184:187], v[214:217], v[18:21]
	v_mfma_f32_16x16x32_bf16 v[18:21], v[188:191], v[218:221], v[18:21]
	v_mfma_f32_16x16x32_bf16 v[2:5], v[184:187], v[222:225], v[2:5]
	v_mfma_f32_16x16x32_bf16 v[2:5], v[188:191], v[226:229], v[2:5]
	s_setprio 0
	s_barrier
	s_add_i32 s58, s58, 2
	s_add_u32 s72, s72, 0x10000
	s_addc_u32 s73, s73, 0
	s_add_u32 s33, s33, 0x10000
	s_addc_u32 s56, s56, 0
	s_cmp_gt_u32 s58, 61
	s_cbranch_scc0 .LBB0_290
	s_and_b64 vcc, exec, s[12:13]
	s_cbranch_vccz .LBB0_293
	s_barrier

; #define PG8_STAGE(bufoff, gbase, voff) do { _Pragma("unroll") for (int _i = 0; _i < 2; ++_i) \
;         __builtin_amdgcn_global_load_lds((const unsigned*)((const char*)(gbase) + (voff)[_i]), (PG8_LAS unsigned*)(lds + (bufoff) + ldsw + _i * 8192), 16, 0, 0); } while (0)
; #define PG8_LDA(dst, b, h) do { _Pragma("unroll") for (int m = 0; m < 4; ++m) _Pragma("unroll") for (int k = 0; k < 2; ++k) dst[m][k] = *(const PG8_LAS bf16x8*)(lds + PG8_SA(b, h) + aoff + m * 2048 + k * 1024); } while (0)
; #define PG8_LDB(dst, b, h) do { _Pragma("unroll") for (int n = 0; n < 2; ++n) _Pragma("unroll") for (int k = 0; k < 2; ++k) dst[n][k] = *(const PG8_LAS bf16x8*)(lds + PG8_SB(b, h) + boff + n * 2048 + k * 1024); } while (0)
; #define PG8_MMA(ai, bj, At, Bt) do { __builtin_amdgcn_s_setprio(1); _Pragma("unroll") for (int m = 0; m < 4; ++m) _Pragma("unroll") for (int n = 0; n < 2; ++n) _Pragma("unroll") for (int k = 0; k < 2; ++k) \
;         acc[ai][bj][m][n] = __builtin_amdgcn_mfma_f32_16x16x32_bf16(Bt[n][k], At[m][k], acc[ai][bj][m][n], 0, 0, 0); __builtin_amdgcn_s_setprio(0); } while (0)
; #define PG8_WAIT_V(n) asm volatile("s_waitcnt vmcnt(" #n ")" ::: "memory")
; #define PG8_WAIT_L(n) asm volatile("s_waitcnt lgkmcnt(" #n ")" ::: "memory")
; template <class Epi, class Sched, bool ALIGN_EPI = false, bool SP2 = false>
; __device__ __forceinline__ void gemm_phase(PG8_LAS unsigned char* lds, const Gemm g, const Sched& S, const Epi& E) {
;     ...
;             const bool last = (t == nt - 2);
;             const char* a1 = cA + (size_t)(t + 1) * kstep;
;             const char* a2 = last ? nA : cA + (size_t)(t + 2) * kstep; const char* b2 = last ? nB : cB + (size_t)(t + 2) * kstep;
;             const char* a3 = a2 + kstep; const char* b3 = b2 + kstep;
;             if (last && has_next) S.a_ready(nxt);
;             if constexpr (SP2) {
;             PG8_LDB(B0, 0, 0); PG8_LDB(B1, 0, 1); PG8_SCHED; PG8_LDA(At, 0, 0); PG8_STAGE(PG8_SA(1, 1), a1 + hstep, voffA);
;             PG8_WAIT_V(8); PG8_WAIT_L(0); PG8_BAR; PG8_MMA(0, 0, At, B0); PG8_MMA(0, 1, At, B1); PG8_BAR; PG8_SCHED;
;             PG8_LDA(At, 0, 1); PG8_STAGE(PG8_SB(0, 0), b2, voffB); PG8_STAGE(PG8_SB(0, 1), b2 + hstep, voffB); PG8_STAGE(PG8_SA(0, 0), a2, voffA);
;             PG8_WAIT_V(8); PG8_WAIT_L(0); PG8_BAR; PG8_MMA(1, 0, At, B0); PG8_MMA(1, 1, At, B1); PG8_BAR; PG8_SCHED;
.LBB0_757:
	ds_read_b128 v[154:157], v149
	ds_read_b128 v[158:161], v149 offset:1024
	ds_read_b128 v[162:165], v149 offset:2048
	ds_read_b128 v[166:169], v149 offset:3072
	ds_read_b128 v[170:173], v150
	ds_read_b128 v[174:177], v150 offset:1024
	ds_read_b128 v[180:183], v150 offset:2048
	ds_read_b128 v[184:187], v150 offset:3072
	s_add_u32 s46, s44, 0x4000
	s_addc_u32 s47, s45, 0
	s_cmp_eq_u32 s70, 60
	s_cselect_b32 s50, s39, s46
	s_cselect_b32 s51, s17, s47
	s_cselect_b32 s48, s41, s68
	s_cselect_b32 s49, s15, s69
	s_add_u32 s46, s50, 0x8000
	s_addc_u32 s47, s51, 0
	s_sub_u32 s46, s44, 0x4000
	s_subb_u32 s47, s45, 0
	s_mov_b32 m0, s57
	s_nop 0
	global_load_lds_dwordx4 v130, s[46:47]
	s_mov_b32 m0, s58
	s_nop 0
	global_load_lds_dwordx4 v134, s[46:47]
	s_add_i32 m0, s26, 0xc000
	ds_read_b128 v[188:191], v151
	ds_read_b128 v[198:201], v151 offset:1024
	ds_read_b128 v[202:205], v151 offset:2048
	ds_read_b128 v[206:209], v151 offset:3072
	ds_read_b128 v[210:213], v151 offset:4096
	ds_read_b128 v[214:217], v151 offset:5120
	ds_read_b128 v[218:221], v151 offset:6144
	ds_read_b128 v[222:225], v151 offset:7168
	global_load_lds_dwordx4 v138, s[44:45]
	s_add_i32 m0, s26, 0xe000
	s_nop 0
	global_load_lds_dwordx4 v140, s[44:45]
	s_waitcnt vmcnt(8)
	s_waitcnt lgkmcnt(0)
	s_barrier
	s_setprio 1
	s_waitcnt lgkmcnt(0)
	v_mfma_f32_16x16x32_bf16 v[126:129], v[154:157], v[188:191], v[126:129]
	v_mfma_f32_16x16x32_bf16 v[126:129], v[158:161], v[198:201], v[126:129]
	v_mfma_f32_16x16x32_bf16 v[110:113], v[154:157], v[202:205], v[110:113]
	v_mfma_f32_16x16x32_bf16 v[110:113], v[158:161], v[206:209], v[110:113]
	v_mfma_f32_16x16x32_bf16 v[94:97], v[154:157], v[210:213], v[94:97]
	v_mfma_f32_16x16x32_bf16 v[94:97], v[158:161], v[214:217], v[94:97]
	v_mfma_f32_16x16x32_bf16 v[78:81], v[154:157], v[218:221], v[78:81]
	v_mfma_f32_16x16x32_bf16 v[78:81], v[158:161], v[222:225], v[78:81]
	v_mfma_f32_16x16x32_bf16 v[122:125], v[162:165], v[188:191], v[122:125]
	v_mfma_f32_16x16x32_bf16 v[122:125], v[166:169], v[198:201], v[122:125]
	v_mfma_f32_16x16x32_bf16 v[106:109], v[162:165], v[202:205], v[106:109]
	v_mfma_f32_16x16x32_bf16 v[106:109], v[166:169], v[206:209], v[106:109]
	v_mfma_f32_16x16x32_bf16 v[90:93], v[162:165], v[210:213], v[90:93]
	v_mfma_f32_16x16x32_bf16 v[90:93], v[166:169], v[214:217], v[90:93]
	v_mfma_f32_16x16x32_bf16 v[74:77], v[162:165], v[218:221], v[74:77]
	v_mfma_f32_16x16x32_bf16 v[74:77], v[166:169], v[222:225], v[74:77]
	s_setprio 0
	s_setprio 1
	v_mfma_f32_16x16x32_bf16 v[118:121], v[170:173], v[188:191], v[118:121]
	v_mfma_f32_16x16x32_bf16 v[118:121], v[174:177], v[198:201], v[118:121]
	v_mfma_f32_16x16x32_bf16 v[102:105], v[170:173], v[202:205], v[102:105]
	v_mfma_f32_16x16x32_bf16 v[102:105], v[174:177], v[206:209], v[102:105]
	v_mfma_f32_16x16x32_bf16 v[86:89], v[170:173], v[210:213], v[86:89]
	v_mfma_f32_16x16x32_bf16 v[86:89], v[174:177], v[214:217], v[86:89]
	v_mfma_f32_16x16x32_bf16 v[70:73], v[170:173], v[218:221], v[70:73]
	v_mfma_f32_16x16x32_bf16 v[70:73], v[174:177], v[222:225], v[70:73]
	v_mfma_f32_16x16x32_bf16 v[114:117], v[180:183], v[188:191], v[114:117]
	v_mfma_f32_16x16x32_bf16 v[114:117], v[184:187], v[198:201], v[114:117]
	v_mfma_f32_16x16x32_bf16 v[98:101], v[180:183], v[202:205], v[98:101]
	v_mfma_f32_16x16x32_bf16 v[98:101], v[184:187], v[206:209], v[98:101]
	v_mfma_f32_16x16x32_bf16 v[82:85], v[180:183], v[210:213], v[82:85]
	v_mfma_f32_16x16x32_bf16 v[82:85], v[184:187], v[214:217], v[82:85]
	v_mfma_f32_16x16x32_bf16 v[66:69], v[180:183], v[218:221], v[66:69]
	v_mfma_f32_16x16x32_bf16 v[66:69], v[184:187], v[222:225], v[66:69]
	s_setprio 0
	s_barrier
	s_add_i32 s71, s59, s3
	s_mov_b32 m0, s71
	ds_read_b128 v[188:191], v151 offset:16384
	ds_read_b128 v[198:201], v151 offset:17408
	ds_read_b128 v[202:205], v151 offset:18432
	ds_read_b128 v[206:209], v151 offset:19456
	ds_read_b128 v[210:213], v151 offset:20480
	ds_read_b128 v[214:217], v151 offset:21504
	ds_read_b128 v[218:221], v151 offset:22528
	ds_read_b128 v[222:225], v151 offset:23552
	global_load_lds_dwordx4 v132, s[48:49]
	s_add_i32 m0, s71, 0x2000
	s_add_u32 s72, s48, 0x4000
	v_lshl_add_u64 v[146:147], s[48:49], 0, v[136:137]
	s_addc_u32 s73, s49, 0
	s_add_i32 s71, s61, s3
	global_load_lds_dwordx4 v[146:147], off
	s_mov_b32 m0, s71
	s_nop 0
	global_load_lds_dwordx4 v132, s[72:73]
	s_add_i32 m0, s71, 0x2000
	s_nop 0
	global_load_lds_dwordx4 v136, s[72:73]
	s_waitcnt vmcnt(6)
	s_waitcnt lgkmcnt(0)
	s_barrier
	s_setprio 1
	s_waitcnt lgkmcnt(0)
	v_mfma_f32_16x16x32_bf16 v[62:65], v[154:157], v[188:191], v[62:65]
	v_mfma_f32_16x16x32_bf16 v[62:65], v[158:161], v[198:201], v[62:65]
	v_mfma_f32_16x16x32_bf16 v[46:49], v[154:157], v[202:205], v[46:49]
	v_mfma_f32_16x16x32_bf16 v[46:49], v[158:161], v[206:209], v[46:49]
	v_mfma_f32_16x16x32_bf16 v[30:33], v[154:157], v[210:213], v[30:33]
	v_mfma_f32_16x16x32_bf16 v[30:33], v[158:161], v[214:217], v[30:33]
	v_mfma_f32_16x16x32_bf16 v[14:17], v[154:157], v[218:221], v[14:17]
	v_mfma_f32_16x16x32_bf16 v[14:17], v[158:161], v[222:225], v[14:17]
	v_mfma_f32_16x16x32_bf16 v[58:61], v[162:165], v[188:191], v[58:61]
	v_mfma_f32_16x16x32_bf16 v[58:61], v[166:169], v[198:201], v[58:61]
	v_mfma_f32_16x16x32_bf16 v[42:45], v[162:165], v[202:205], v[42:45]
	v_mfma_f32_16x16x32_bf16 v[42:45], v[166:169], v[206:209], v[42:45]
	v_mfma_f32_16x16x32_bf16 v[26:29], v[162:165], v[210:213], v[26:29]
	v_mfma_f32_16x16x32_bf16 v[26:29], v[166:169], v[214:217], v[26:29]
	v_mfma_f32_16x16x32_bf16 v[10:13], v[162:165], v[218:221], v[10:13]
	v_mfma_f32_16x16x32_bf16 v[10:13], v[166:169], v[222:225], v[10:13]
	s_setprio 0
	s_setprio 1
	v_mfma_f32_16x16x32_bf16 v[54:57], v[170:173], v[188:191], v[54:57]
	v_mfma_f32_16x16x32_bf16 v[54:57], v[174:177], v[198:201], v[54:57]
	v_mfma_f32_16x16x32_bf16 v[38:41], v[170:173], v[202:205], v[38:41]
	v_mfma_f32_16x16x32_bf16 v[38:41], v[174:177], v[206:209], v[38:41]
	v_mfma_f32_16x16x32_bf16 v[22:25], v[170:173], v[210:213], v[22:25]
	v_mfma_f32_16x16x32_bf16 v[22:25], v[174:177], v[214:217], v[22:25]
	v_mfma_f32_16x16x32_bf16 v[6:9], v[170:173], v[218:221], v[6:9]
	v_mfma_f32_16x16x32_bf16 v[6:9], v[174:177], v[222:225], v[6:9]
	v_mfma_f32_16x16x32_bf16 v[50:53], v[180:183], v[188:191], v[50:53]
	v_mfma_f32_16x16x32_bf16 v[50:53], v[184:187], v[198:201], v[50:53]
	v_mfma_f32_16x16x32_bf16 v[34:37], v[180:183], v[202:205], v[34:37]
	v_mfma_f32_16x16x32_bf16 v[34:37], v[184:187], v[206:209], v[34:37]
	v_mfma_f32_16x16x32_bf16 v[18:21], v[180:183], v[210:213], v[18:21]
	v_mfma_f32_16x16x32_bf16 v[18:21], v[184:187], v[214:217], v[18:21]
	v_mfma_f32_16x16x32_bf16 v[2:5], v[180:183], v[218:221], v[2:5]
	v_mfma_f32_16x16x32_bf16 v[2:5], v[184:187], v[222:225], v[2:5]
	s_setprio 0
	s_barrier
; #define PG8_STAGE(bufoff, gbase, voff) do { _Pragma("unroll") for (int _i = 0; _i < 2; ++_i) \
;         __builtin_amdgcn_global_load_lds((const unsigned*)((const char*)(gbase) + (voff)[_i]), (PG8_LAS unsigned*)(lds + (bufoff) + ldsw + _i * 8192), 16, 0, 0); } while (0)
; #define PG8_LDA(dst, b, h) do { _Pragma("unroll") for (int m = 0; m < 4; ++m) _Pragma("unroll") for (int k = 0; k < 2; ++k) dst[m][k] = *(const PG8_LAS bf16x8*)(lds + PG8_SA(b, h) + aoff + m * 2048 + k * 1024); } while (0)
; #define PG8_LDB(dst, b, h) do { _Pragma("unroll") for (int n = 0; n < 2; ++n) _Pragma("unroll") for (int k = 0; k < 2; ++k) dst[n][k] = *(const PG8_LAS bf16x8*)(lds + PG8_SB(b, h) + boff + n * 2048 + k * 1024); } while (0)
; #define PG8_MMA(ai, bj, At, Bt) do { __builtin_amdgcn_s_setprio(1); _Pragma("unroll") for (int m = 0; m < 4; ++m) _Pragma("unroll") for (int n = 0; n < 2; ++n) _Pragma("unroll") for (int k = 0; k < 2; ++k) \
;         acc[ai][bj][m][n] = __builtin_amdgcn_mfma_f32_16x16x32_bf16(Bt[n][k], At[m][k], acc[ai][bj][m][n], 0, 0, 0); __builtin_amdgcn_s_setprio(0); } while (0)
; #define PG8_WAIT_V(n) asm volatile("s_waitcnt vmcnt(" #n ")" ::: "memory")
; #define PG8_WAIT_L(n) asm volatile("s_waitcnt lgkmcnt(" #n ")" ::: "memory")
; #define PG8_BAR __builtin_amdgcn_s_barrier()
; #define PG8_SCHED __builtin_amdgcn_sched_barrier(0)
; template <class Epi, class Sched, bool ALIGN_EPI = false, bool SP2 = false>
; __device__ __forceinline__ void gemm_phase(PG8_LAS unsigned char* lds, const Gemm g, const Sched& S, const Epi& E) {
;     ...
;             PG8_LDB(B0, 1, 0); PG8_LDB(B1, 1, 1); PG8_SCHED; PG8_LDA(At, 1, 0); PG8_STAGE(PG8_SA(0, 1), a2 + hstep, voffA);
;             PG8_WAIT_V(8); PG8_WAIT_L(0); PG8_BAR; PG8_MMA(0, 0, At, B0); PG8_MMA(0, 1, At, B1); PG8_BAR; PG8_SCHED;
;             PG8_LDA(At, 1, 1); PG8_STAGE(PG8_SB(1, 0), b3, voffB); PG8_STAGE(PG8_SB(1, 1), b3 + hstep, voffB); PG8_STAGE(PG8_SA(1, 0), a3, voffA);
;             PG8_WAIT_V(8); PG8_WAIT_L(0); PG8_BAR; PG8_MMA(1, 0, At, B0); PG8_MMA(1, 1, At, B1); PG8_BAR; PG8_SCHED;
	s_add_i32 s71, 0, 0x18000
	v_add_u32_e32 v146, s71, v1
	s_add_i32 s72, 0, 0x1c000
	ds_read_b128 v[154:157], v146
	ds_read_b128 v[158:161], v146 offset:1024
	ds_read_b128 v[162:165], v146 offset:2048
	ds_read_b128 v[166:169], v146 offset:3072
	v_add_u32_e32 v146, s72, v1
	ds_read_b128 v[170:173], v146
	ds_read_b128 v[174:177], v146 offset:1024
	ds_read_b128 v[180:183], v146 offset:2048
	ds_read_b128 v[184:187], v146 offset:3072
	s_mov_b32 m0, s26
	s_nop 0
	global_load_lds_dwordx4 v130, s[50:51]
	s_mov_b32 m0, s27
	s_nop 0
	global_load_lds_dwordx4 v134, s[50:51]
	s_add_u32 s50, s50, 0x4000
	s_addc_u32 s51, s51, 0
	s_mov_b32 m0, s28
	ds_read_b128 v[188:191], v151 offset:32768
	ds_read_b128 v[198:201], v151 offset:33792
	ds_read_b128 v[202:205], v151 offset:34816
	ds_read_b128 v[206:209], v151 offset:35840
	ds_read_b128 v[210:213], v151 offset:36864
	ds_read_b128 v[214:217], v151 offset:37888
	ds_read_b128 v[218:221], v151 offset:38912
	ds_read_b128 v[222:225], v151 offset:39936
	global_load_lds_dwordx4 v130, s[50:51]
	s_mov_b32 m0, s29
	s_nop 0
	global_load_lds_dwordx4 v134, s[50:51]
	s_waitcnt vmcnt(8)
	s_waitcnt lgkmcnt(0)
	s_barrier
	s_setprio 1
	s_waitcnt lgkmcnt(0)
	v_mfma_f32_16x16x32_bf16 v[126:129], v[154:157], v[188:191], v[126:129]
	v_mfma_f32_16x16x32_bf16 v[126:129], v[158:161], v[198:201], v[126:129]
	v_mfma_f32_16x16x32_bf16 v[110:113], v[154:157], v[202:205], v[110:113]
	v_mfma_f32_16x16x32_bf16 v[110:113], v[158:161], v[206:209], v[110:113]
	v_mfma_f32_16x16x32_bf16 v[94:97], v[154:157], v[210:213], v[94:97]
	v_mfma_f32_16x16x32_bf16 v[94:97], v[158:161], v[214:217], v[94:97]
	v_mfma_f32_16x16x32_bf16 v[78:81], v[154:157], v[218:221], v[78:81]
	v_mfma_f32_16x16x32_bf16 v[78:81], v[158:161], v[222:225], v[78:81]
	v_mfma_f32_16x16x32_bf16 v[122:125], v[162:165], v[188:191], v[122:125]
	v_mfma_f32_16x16x32_bf16 v[122:125], v[166:169], v[198:201], v[122:125]
	v_mfma_f32_16x16x32_bf16 v[106:109], v[162:165], v[202:205], v[106:109]
	v_mfma_f32_16x16x32_bf16 v[106:109], v[166:169], v[206:209], v[106:109]
	v_mfma_f32_16x16x32_bf16 v[90:93], v[162:165], v[210:213], v[90:93]
	v_mfma_f32_16x16x32_bf16 v[90:93], v[166:169], v[214:217], v[90:93]
	v_mfma_f32_16x16x32_bf16 v[74:77], v[162:165], v[218:221], v[74:77]
	v_mfma_f32_16x16x32_bf16 v[74:77], v[166:169], v[222:225], v[74:77]
	s_setprio 0
	s_setprio 1
	v_mfma_f32_16x16x32_bf16 v[118:121], v[170:173], v[188:191], v[118:121]
	v_mfma_f32_16x16x32_bf16 v[118:121], v[174:177], v[198:201], v[118:121]
	v_mfma_f32_16x16x32_bf16 v[102:105], v[170:173], v[202:205], v[102:105]
	v_mfma_f32_16x16x32_bf16 v[102:105], v[174:177], v[206:209], v[102:105]
	v_mfma_f32_16x16x32_bf16 v[86:89], v[170:173], v[210:213], v[86:89]
	v_mfma_f32_16x16x32_bf16 v[86:89], v[174:177], v[214:217], v[86:89]
	v_mfma_f32_16x16x32_bf16 v[70:73], v[170:173], v[218:221], v[70:73]
	v_mfma_f32_16x16x32_bf16 v[70:73], v[174:177], v[222:225], v[70:73]
	v_mfma_f32_16x16x32_bf16 v[114:117], v[180:183], v[188:191], v[114:117]
	v_mfma_f32_16x16x32_bf16 v[114:117], v[184:187], v[198:201], v[114:117]
	v_mfma_f32_16x16x32_bf16 v[98:101], v[180:183], v[202:205], v[98:101]
	v_mfma_f32_16x16x32_bf16 v[98:101], v[184:187], v[206:209], v[98:101]
	v_mfma_f32_16x16x32_bf16 v[82:85], v[180:183], v[210:213], v[82:85]
	v_mfma_f32_16x16x32_bf16 v[82:85], v[184:187], v[214:217], v[82:85]
	v_mfma_f32_16x16x32_bf16 v[66:69], v[180:183], v[218:221], v[66:69]
	v_mfma_f32_16x16x32_bf16 v[66:69], v[184:187], v[222:225], v[66:69]
	s_setprio 0
	s_barrier
	s_add_u32 s50, s48, 0x8000
	s_addc_u32 s51, s49, 0
	s_add_i32 s71, s71, s3
	s_mov_b32 m0, s71
	ds_read_b128 v[188:191], v151 offset:49152
	ds_read_b128 v[198:201], v151 offset:50176
	ds_read_b128 v[202:205], v151 offset:51200
	ds_read_b128 v[206:209], v151 offset:52224
	ds_read_b128 v[210:213], v151 offset:53248
	ds_read_b128 v[214:217], v151 offset:54272
	ds_read_b128 v[218:221], v151 offset:55296
	ds_read_b128 v[222:225], v151 offset:56320
	global_load_lds_dwordx4 v132, s[50:51]
	s_add_i32 m0, s71, 0x2000
	s_add_u32 s48, s48, 0xc000
	v_lshl_add_u64 v[146:147], s[50:51], 0, v[136:137]
	s_addc_u32 s49, s49, 0
	s_add_i32 s50, s72, s3
	global_load_lds_dwordx4 v[146:147], off
	s_mov_b32 m0, s50
	s_nop 0
	global_load_lds_dwordx4 v132, s[48:49]
	s_add_i32 m0, s50, 0x2000
	s_nop 0
	global_load_lds_dwordx4 v136, s[48:49]
	s_waitcnt vmcnt(6)
	s_waitcnt lgkmcnt(0)
	s_barrier
	s_setprio 1
	s_waitcnt lgkmcnt(0)
	v_mfma_f32_16x16x32_bf16 v[62:65], v[154:157], v[188:191], v[62:65]
	v_mfma_f32_16x16x32_bf16 v[62:65], v[158:161], v[198:201], v[62:65]
	v_mfma_f32_16x16x32_bf16 v[46:49], v[154:157], v[202:205], v[46:49]
	v_mfma_f32_16x16x32_bf16 v[46:49], v[158:161], v[206:209], v[46:49]
	v_mfma_f32_16x16x32_bf16 v[30:33], v[154:157], v[210:213], v[30:33]
	v_mfma_f32_16x16x32_bf16 v[30:33], v[158:161], v[214:217], v[30:33]
	v_mfma_f32_16x16x32_bf16 v[14:17], v[154:157], v[218:221], v[14:17]
	v_mfma_f32_16x16x32_bf16 v[14:17], v[158:161], v[222:225], v[14:17]
	v_mfma_f32_16x16x32_bf16 v[58:61], v[162:165], v[188:191], v[58:61]
	v_mfma_f32_16x16x32_bf16 v[58:61], v[166:169], v[198:201], v[58:61]
	v_mfma_f32_16x16x32_bf16 v[42:45], v[162:165], v[202:205], v[42:45]
	v_mfma_f32_16x16x32_bf16 v[42:45], v[166:169], v[206:209], v[42:45]
	v_mfma_f32_16x16x32_bf16 v[26:29], v[162:165], v[210:213], v[26:29]
	v_mfma_f32_16x16x32_bf16 v[26:29], v[166:169], v[214:217], v[26:29]
	v_mfma_f32_16x16x32_bf16 v[10:13], v[162:165], v[218:221], v[10:13]
	v_mfma_f32_16x16x32_bf16 v[10:13], v[166:169], v[222:225], v[10:13]
	s_setprio 0
	s_setprio 1
	v_mfma_f32_16x16x32_bf16 v[54:57], v[170:173], v[188:191], v[54:57]
	v_mfma_f32_16x16x32_bf16 v[54:57], v[174:177], v[198:201], v[54:57]
	v_mfma_f32_16x16x32_bf16 v[38:41], v[170:173], v[202:205], v[38:41]
	v_mfma_f32_16x16x32_bf16 v[38:41], v[174:177], v[206:209], v[38:41]
	v_mfma_f32_16x16x32_bf16 v[22:25], v[170:173], v[210:213], v[22:25]
	v_mfma_f32_16x16x32_bf16 v[22:25], v[174:177], v[214:217], v[22:25]
	v_mfma_f32_16x16x32_bf16 v[6:9], v[170:173], v[218:221], v[6:9]
	v_mfma_f32_16x16x32_bf16 v[6:9], v[174:177], v[222:225], v[6:9]
	v_mfma_f32_16x16x32_bf16 v[50:53], v[180:183], v[188:191], v[50:53]
	v_mfma_f32_16x16x32_bf16 v[50:53], v[184:187], v[198:201], v[50:53]
	v_mfma_f32_16x16x32_bf16 v[34:37], v[180:183], v[202:205], v[34:37]
	v_mfma_f32_16x16x32_bf16 v[34:37], v[184:187], v[206:209], v[34:37]
	v_mfma_f32_16x16x32_bf16 v[18:21], v[180:183], v[210:213], v[18:21]
	v_mfma_f32_16x16x32_bf16 v[18:21], v[184:187], v[214:217], v[18:21]
	v_mfma_f32_16x16x32_bf16 v[2:5], v[180:183], v[218:221], v[2:5]
	v_mfma_f32_16x16x32_bf16 v[2:5], v[184:187], v[222:225], v[2:5]
	s_setprio 0
	s_barrier
	s_add_i32 s70, s70, 2
	s_add_u32 s44, s44, 0x10000
	s_addc_u32 s45, s45, 0
	s_add_u32 s68, s68, 0x10000
	s_addc_u32 s69, s69, 0
	s_cmp_gt_u32 s70, 61
	s_cbranch_scc0 .LBB0_757
	s_and_b64 vcc, exec, s[12:13]
	s_cbranch_vccz .LBB0_760
	s_barrier

; #define PG8_STAGE(bufoff, gbase, voff) do { _Pragma("unroll") for (int _i = 0; _i < 2; ++_i) \
;         __builtin_amdgcn_global_load_lds((const unsigned*)((const char*)(gbase) + (voff)[_i]), (PG8_LAS unsigned*)(lds + (bufoff) + ldsw + _i * 8192), 16, 0, 0); } while (0)
; #define PG8_LDA(dst, b, h) do { _Pragma("unroll") for (int m = 0; m < 4; ++m) _Pragma("unroll") for (int k = 0; k < 2; ++k) dst[m][k] = *(const PG8_LAS bf16x8*)(lds + PG8_SA(b, h) + aoff + m * 2048 + k * 1024); } while (0)
; #define PG8_LDB(dst, b, h) do { _Pragma("unroll") for (int n = 0; n < 2; ++n) _Pragma("unroll") for (int k = 0; k < 2; ++k) dst[n][k] = *(const PG8_LAS bf16x8*)(lds + PG8_SB(b, h) + boff + n * 2048 + k * 1024); } while (0)
; #define PG8_MMA(ai, bj, At, Bt) do { __builtin_amdgcn_s_setprio(1); _Pragma("unroll") for (int m = 0; m < 4; ++m) _Pragma("unroll") for (int n = 0; n < 2; ++n) _Pragma("unroll") for (int k = 0; k < 2; ++k) \
;         acc[ai][bj][m][n] = __builtin_amdgcn_mfma_f32_16x16x32_bf16(Bt[n][k], At[m][k], acc[ai][bj][m][n], 0, 0, 0); __builtin_amdgcn_s_setprio(0); } while (0)
; #define PG8_WAIT_V(n) asm volatile("s_waitcnt vmcnt(" #n ")" ::: "memory")
; #define PG8_WAIT_L(n) asm volatile("s_waitcnt lgkmcnt(" #n ")" ::: "memory")
; template <class Epi, class Sched, bool ALIGN_EPI = false, bool SP2 = false>
; __device__ __forceinline__ void gemm_phase(PG8_LAS unsigned char* lds, const Gemm g, const Sched& S, const Epi& E) {
;     ...
;             const bool last = (t == nt - 2);
;             const char* a1 = cA + (size_t)(t + 1) * kstep;
;             const char* a2 = last ? nA : cA + (size_t)(t + 2) * kstep; const char* b2 = last ? nB : cB + (size_t)(t + 2) * kstep;
;             const char* a3 = a2 + kstep; const char* b3 = b2 + kstep;
;             if (last && has_next) S.a_ready(nxt);
;             if constexpr (SP2) {
;             PG8_LDB(B0, 0, 0); PG8_LDB(B1, 0, 1); PG8_SCHED; PG8_LDA(At, 0, 0); PG8_STAGE(PG8_SA(1, 1), a1 + hstep, voffA);
;             PG8_WAIT_V(8); PG8_WAIT_L(0); PG8_BAR; PG8_MMA(0, 0, At, B0); PG8_MMA(0, 1, At, B1); PG8_BAR; PG8_SCHED;
;             PG8_LDA(At, 0, 1); PG8_STAGE(PG8_SB(0, 0), b2, voffB); PG8_STAGE(PG8_SB(0, 1), b2 + hstep, voffB); PG8_STAGE(PG8_SA(0, 0), a2, voffA);
;             PG8_WAIT_V(8); PG8_WAIT_L(0); PG8_BAR; PG8_MMA(1, 0, At, B0); PG8_MMA(1, 1, At, B1); PG8_BAR; PG8_SCHED;
.LBB0_840:
	ds_read_b128 v[148:151], v153
	ds_read_b128 v[158:161], v153 offset:1024
	ds_read_b128 v[162:165], v153 offset:2048
	ds_read_b128 v[166:169], v153 offset:3072
	ds_read_b128 v[170:173], v154
	ds_read_b128 v[174:177], v154 offset:1024
	ds_read_b128 v[180:183], v154 offset:2048
	ds_read_b128 v[184:187], v154 offset:3072
	s_add_u32 s42, s40, 0x4000
	s_addc_u32 s43, s41, 0
	s_cmp_eq_u32 s69, 60
	s_cselect_b32 s46, s65, s42
	s_cselect_b32 s47, s23, s43
	s_cselect_b32 s44, s66, s67
	s_cselect_b32 s45, s17, s68
	s_add_u32 s42, s46, 0x8000
	s_addc_u32 s43, s47, 0
	s_sub_u32 s42, s40, 0x4000
	s_subb_u32 s43, s41, 0
	s_mov_b32 m0, s50
	s_nop 0
	global_load_lds_dwordx4 v130, s[42:43]
	s_mov_b32 m0, s51
	s_nop 0
	global_load_lds_dwordx4 v134, s[42:43]
	s_add_i32 m0, s28, 0xc000
	ds_read_b128 v[188:191], v155
	ds_read_b128 v[198:201], v155 offset:1024
	ds_read_b128 v[202:205], v155 offset:2048
	ds_read_b128 v[206:209], v155 offset:3072
	ds_read_b128 v[210:213], v155 offset:4096
	ds_read_b128 v[214:217], v155 offset:5120
	ds_read_b128 v[218:221], v155 offset:6144
	ds_read_b128 v[222:225], v155 offset:7168
	global_load_lds_dwordx4 v140, s[40:41]
	s_add_i32 m0, s28, 0xe000
	s_nop 0
	global_load_lds_dwordx4 v142, s[40:41]
	s_waitcnt vmcnt(8)
	s_waitcnt lgkmcnt(0)
	s_barrier
	s_setprio 1
	s_waitcnt lgkmcnt(0)
	v_mfma_f32_16x16x32_bf16 v[126:129], v[148:151], v[188:191], v[126:129]
	v_mfma_f32_16x16x32_bf16 v[126:129], v[158:161], v[198:201], v[126:129]
	v_mfma_f32_16x16x32_bf16 v[110:113], v[148:151], v[202:205], v[110:113]
	v_mfma_f32_16x16x32_bf16 v[110:113], v[158:161], v[206:209], v[110:113]
	v_mfma_f32_16x16x32_bf16 v[94:97], v[148:151], v[210:213], v[94:97]
	v_mfma_f32_16x16x32_bf16 v[94:97], v[158:161], v[214:217], v[94:97]
	v_mfma_f32_16x16x32_bf16 v[78:81], v[148:151], v[218:221], v[78:81]
	v_mfma_f32_16x16x32_bf16 v[78:81], v[158:161], v[222:225], v[78:81]
	v_mfma_f32_16x16x32_bf16 v[122:125], v[162:165], v[188:191], v[122:125]
	v_mfma_f32_16x16x32_bf16 v[122:125], v[166:169], v[198:201], v[122:125]
	v_mfma_f32_16x16x32_bf16 v[106:109], v[162:165], v[202:205], v[106:109]
	v_mfma_f32_16x16x32_bf16 v[106:109], v[166:169], v[206:209], v[106:109]
	v_mfma_f32_16x16x32_bf16 v[90:93], v[162:165], v[210:213], v[90:93]
	v_mfma_f32_16x16x32_bf16 v[90:93], v[166:169], v[214:217], v[90:93]
	v_mfma_f32_16x16x32_bf16 v[74:77], v[162:165], v[218:221], v[74:77]
	v_mfma_f32_16x16x32_bf16 v[74:77], v[166:169], v[222:225], v[74:77]
	s_setprio 0
	s_setprio 1
	v_mfma_f32_16x16x32_bf16 v[118:121], v[170:173], v[188:191], v[118:121]
	v_mfma_f32_16x16x32_bf16 v[118:121], v[174:177], v[198:201], v[118:121]
	v_mfma_f32_16x16x32_bf16 v[102:105], v[170:173], v[202:205], v[102:105]
	v_mfma_f32_16x16x32_bf16 v[102:105], v[174:177], v[206:209], v[102:105]
	v_mfma_f32_16x16x32_bf16 v[86:89], v[170:173], v[210:213], v[86:89]
	v_mfma_f32_16x16x32_bf16 v[86:89], v[174:177], v[214:217], v[86:89]
	v_mfma_f32_16x16x32_bf16 v[70:73], v[170:173], v[218:221], v[70:73]
	v_mfma_f32_16x16x32_bf16 v[70:73], v[174:177], v[222:225], v[70:73]
	v_mfma_f32_16x16x32_bf16 v[114:117], v[180:183], v[188:191], v[114:117]
	v_mfma_f32_16x16x32_bf16 v[114:117], v[184:187], v[198:201], v[114:117]
	v_mfma_f32_16x16x32_bf16 v[98:101], v[180:183], v[202:205], v[98:101]
	v_mfma_f32_16x16x32_bf16 v[98:101], v[184:187], v[206:209], v[98:101]
	v_mfma_f32_16x16x32_bf16 v[82:85], v[180:183], v[210:213], v[82:85]
	v_mfma_f32_16x16x32_bf16 v[82:85], v[184:187], v[214:217], v[82:85]
	v_mfma_f32_16x16x32_bf16 v[66:69], v[180:183], v[218:221], v[66:69]
	v_mfma_f32_16x16x32_bf16 v[66:69], v[184:187], v[222:225], v[66:69]
	s_setprio 0
	s_barrier
	s_add_i32 s70, s56, s3
	s_mov_b32 m0, s70
	ds_read_b128 v[188:191], v155 offset:16384
	ds_read_b128 v[198:201], v155 offset:17408
	ds_read_b128 v[202:205], v155 offset:18432
	ds_read_b128 v[206:209], v155 offset:19456
	ds_read_b128 v[210:213], v155 offset:20480
	ds_read_b128 v[214:217], v155 offset:21504
	ds_read_b128 v[218:221], v155 offset:22528
	ds_read_b128 v[222:225], v155 offset:23552
	global_load_lds_dwordx4 v132, s[44:45]
	s_add_i32 m0, s70, 0x2000
	s_add_u32 s70, s44, 0x4000
	v_lshl_add_u64 v[226:227], s[44:45], 0, v[136:137]
	s_addc_u32 s71, s45, 0
	s_add_i32 s72, s57, s3
	global_load_lds_dwordx4 v[226:227], off
	s_mov_b32 m0, s72
	s_nop 0
	global_load_lds_dwordx4 v132, s[70:71]
	s_add_i32 m0, s72, 0x2000
	s_nop 0
	global_load_lds_dwordx4 v136, s[70:71]
	s_waitcnt vmcnt(6)
	s_waitcnt lgkmcnt(0)
	s_barrier
	s_setprio 1
	s_waitcnt lgkmcnt(0)
	v_mfma_f32_16x16x32_bf16 v[62:65], v[148:151], v[188:191], v[62:65]
	v_mfma_f32_16x16x32_bf16 v[62:65], v[158:161], v[198:201], v[62:65]
	v_mfma_f32_16x16x32_bf16 v[46:49], v[148:151], v[202:205], v[46:49]
	v_mfma_f32_16x16x32_bf16 v[46:49], v[158:161], v[206:209], v[46:49]
	v_mfma_f32_16x16x32_bf16 v[30:33], v[148:151], v[210:213], v[30:33]
	v_mfma_f32_16x16x32_bf16 v[30:33], v[158:161], v[214:217], v[30:33]
	v_mfma_f32_16x16x32_bf16 v[14:17], v[148:151], v[218:221], v[14:17]
	v_mfma_f32_16x16x32_bf16 v[14:17], v[158:161], v[222:225], v[14:17]
	v_mfma_f32_16x16x32_bf16 v[58:61], v[162:165], v[188:191], v[58:61]
	v_mfma_f32_16x16x32_bf16 v[58:61], v[166:169], v[198:201], v[58:61]
	v_mfma_f32_16x16x32_bf16 v[42:45], v[162:165], v[202:205], v[42:45]
	v_mfma_f32_16x16x32_bf16 v[42:45], v[166:169], v[206:209], v[42:45]
	v_mfma_f32_16x16x32_bf16 v[26:29], v[162:165], v[210:213], v[26:29]
	v_mfma_f32_16x16x32_bf16 v[26:29], v[166:169], v[214:217], v[26:29]
	v_mfma_f32_16x16x32_bf16 v[10:13], v[162:165], v[218:221], v[10:13]
	v_mfma_f32_16x16x32_bf16 v[10:13], v[166:169], v[222:225], v[10:13]
	s_setprio 0
	s_setprio 1
	v_mfma_f32_16x16x32_bf16 v[54:57], v[170:173], v[188:191], v[54:57]
	v_mfma_f32_16x16x32_bf16 v[54:57], v[174:177], v[198:201], v[54:57]
	v_mfma_f32_16x16x32_bf16 v[38:41], v[170:173], v[202:205], v[38:41]
	v_mfma_f32_16x16x32_bf16 v[38:41], v[174:177], v[206:209], v[38:41]
	v_mfma_f32_16x16x32_bf16 v[22:25], v[170:173], v[210:213], v[22:25]
	v_mfma_f32_16x16x32_bf16 v[22:25], v[174:177], v[214:217], v[22:25]
	v_mfma_f32_16x16x32_bf16 v[6:9], v[170:173], v[218:221], v[6:9]
	v_mfma_f32_16x16x32_bf16 v[6:9], v[174:177], v[222:225], v[6:9]
	v_mfma_f32_16x16x32_bf16 v[50:53], v[180:183], v[188:191], v[50:53]
	v_mfma_f32_16x16x32_bf16 v[50:53], v[184:187], v[198:201], v[50:53]
	v_mfma_f32_16x16x32_bf16 v[34:37], v[180:183], v[202:205], v[34:37]
	v_mfma_f32_16x16x32_bf16 v[34:37], v[184:187], v[206:209], v[34:37]
	v_mfma_f32_16x16x32_bf16 v[18:21], v[180:183], v[210:213], v[18:21]
	v_mfma_f32_16x16x32_bf16 v[18:21], v[184:187], v[214:217], v[18:21]
	v_mfma_f32_16x16x32_bf16 v[2:5], v[180:183], v[218:221], v[2:5]
	v_mfma_f32_16x16x32_bf16 v[2:5], v[184:187], v[222:225], v[2:5]
	s_setprio 0
	s_barrier
; #define PG8_STAGE(bufoff, gbase, voff) do { _Pragma("unroll") for (int _i = 0; _i < 2; ++_i) \
;         __builtin_amdgcn_global_load_lds((const unsigned*)((const char*)(gbase) + (voff)[_i]), (PG8_LAS unsigned*)(lds + (bufoff) + ldsw + _i * 8192), 16, 0, 0); } while (0)
; #define PG8_LDA(dst, b, h) do { _Pragma("unroll") for (int m = 0; m < 4; ++m) _Pragma("unroll") for (int k = 0; k < 2; ++k) dst[m][k] = *(const PG8_LAS bf16x8*)(lds + PG8_SA(b, h) + aoff + m * 2048 + k * 1024); } while (0)
; #define PG8_LDB(dst, b, h) do { _Pragma("unroll") for (int n = 0; n < 2; ++n) _Pragma("unroll") for (int k = 0; k < 2; ++k) dst[n][k] = *(const PG8_LAS bf16x8*)(lds + PG8_SB(b, h) + boff + n * 2048 + k * 1024); } while (0)
; #define PG8_WAIT_V(n) asm volatile("s_waitcnt vmcnt(" #n ")" ::: "memory")
; template <class Epi, class Sched, bool ALIGN_EPI = false, bool SP2 = false>
; __device__ __forceinline__ void gemm_phase(PG8_LAS unsigned char* lds, const Gemm g, const Sched& S, const Epi& E) {
;     ...
;             const char* a1 = cA + (size_t)(t + 1) * kstep;
;             const char* a2 = last ? nA : cA + (size_t)(t + 2) * kstep; const char* b2 = last ? nB : cB + (size_t)(t + 2) * kstep;
;             const char* a3 = a2 + kstep; const char* b3 = b2 + kstep;
;             if (last && has_next) S.a_ready(nxt);
;             if constexpr (SP2) {
;             PG8_LDB(B0, 0, 0); PG8_LDB(B1, 0, 1); PG8_SCHED; PG8_LDA(At, 0, 0); PG8_STAGE(PG8_SA(1, 1), a1 + hstep, voffA);
;             PG8_WAIT_V(8); PG8_WAIT_L(0); PG8_BAR; PG8_MMA(0, 0, At, B0); PG8_MMA(0, 1, At, B1); PG8_BAR; PG8_SCHED;
;             PG8_LDA(At, 0, 1); PG8_STAGE(PG8_SB(0, 0), b2, voffB); PG8_STAGE(PG8_SB(0, 1), b2 + hstep, voffB); PG8_STAGE(PG8_SA(0, 0), a2, voffA);
;             PG8_WAIT_V(8); PG8_WAIT_L(0); PG8_BAR; PG8_MMA(1, 0, At, B0); PG8_MMA(1, 1, At, B1); PG8_BAR; PG8_SCHED;
;             PG8_LDB(B0, 1, 0); PG8_LDB(B1, 1, 1); PG8_SCHED; PG8_LDA(At, 1, 0); PG8_STAGE(PG8_SA(0, 1), a2 + hstep, voffA);
;             PG8_WAIT_V(8); PG8_WAIT_L(0); PG8_BAR; PG8_MMA(0, 0, At, B0); PG8_MMA(0, 1, At, B1); PG8_BAR; PG8_SCHED;
;             PG8_LDA(At, 1, 1); PG8_STAGE(PG8_SB(1, 0), b3, voffB); PG8_STAGE(PG8_SB(1, 1), b3 + hstep, voffB); PG8_STAGE(PG8_SA(1, 0), a3, voffA);
;             PG8_WAIT_V(8); PG8_WAIT_L(0); PG8_BAR; PG8_MMA(1, 0, At, B0); PG8_MMA(1, 1, At, B1); PG8_BAR; PG8_SCHED;
	s_add_i32 s70, 0, 0x18000
	v_add_u32_e32 v138, s70, v1
	s_add_i32 s71, 0, 0x1c000
	ds_read_b128 v[148:151], v138
	ds_read_b128 v[158:161], v138 offset:1024
	ds_read_b128 v[162:165], v138 offset:2048
	ds_read_b128 v[166:169], v138 offset:3072
	v_add_u32_e32 v138, s71, v1
	ds_read_b128 v[170:173], v138
	ds_read_b128 v[174:177], v138 offset:1024
	ds_read_b128 v[180:183], v138 offset:2048
	ds_read_b128 v[184:187], v138 offset:3072
	s_mov_b32 m0, s28
	s_nop 0
	global_load_lds_dwordx4 v130, s[46:47]
	s_mov_b32 m0, s29
	s_nop 0
	global_load_lds_dwordx4 v134, s[46:47]
	s_add_u32 s46, s46, 0x4000
	s_addc_u32 s47, s47, 0
	s_mov_b32 m0, s30
	ds_read_b128 v[188:191], v155 offset:32768
	ds_read_b128 v[198:201], v155 offset:33792
	ds_read_b128 v[202:205], v155 offset:34816
	ds_read_b128 v[206:209], v155 offset:35840
	ds_read_b128 v[210:213], v155 offset:36864
	ds_read_b128 v[214:217], v155 offset:37888
	ds_read_b128 v[218:221], v155 offset:38912
	ds_read_b128 v[222:225], v155 offset:39936
	global_load_lds_dwordx4 v130, s[46:47]
	s_mov_b32 m0, s31
	s_nop 0
	global_load_lds_dwordx4 v134, s[46:47]
	s_waitcnt vmcnt(8)
	s_waitcnt lgkmcnt(0)
	s_barrier
	s_setprio 1
	s_waitcnt lgkmcnt(0)
	v_mfma_f32_16x16x32_bf16 v[126:129], v[148:151], v[188:191], v[126:129]
	v_mfma_f32_16x16x32_bf16 v[126:129], v[158:161], v[198:201], v[126:129]
	v_mfma_f32_16x16x32_bf16 v[110:113], v[148:151], v[202:205], v[110:113]
	v_mfma_f32_16x16x32_bf16 v[110:113], v[158:161], v[206:209], v[110:113]
	v_mfma_f32_16x16x32_bf16 v[94:97], v[148:151], v[210:213], v[94:97]
	v_mfma_f32_16x16x32_bf16 v[94:97], v[158:161], v[214:217], v[94:97]
	v_mfma_f32_16x16x32_bf16 v[78:81], v[148:151], v[218:221], v[78:81]
	v_mfma_f32_16x16x32_bf16 v[78:81], v[158:161], v[222:225], v[78:81]
	v_mfma_f32_16x16x32_bf16 v[122:125], v[162:165], v[188:191], v[122:125]
	v_mfma_f32_16x16x32_bf16 v[122:125], v[166:169], v[198:201], v[122:125]
	v_mfma_f32_16x16x32_bf16 v[106:109], v[162:165], v[202:205], v[106:109]
	v_mfma_f32_16x16x32_bf16 v[106:109], v[166:169], v[206:209], v[106:109]
	v_mfma_f32_16x16x32_bf16 v[90:93], v[162:165], v[210:213], v[90:93]
	v_mfma_f32_16x16x32_bf16 v[90:93], v[166:169], v[214:217], v[90:93]
	v_mfma_f32_16x16x32_bf16 v[74:77], v[162:165], v[218:221], v[74:77]
	v_mfma_f32_16x16x32_bf16 v[74:77], v[166:169], v[222:225], v[74:77]
	s_setprio 0
	s_setprio 1
	v_mfma_f32_16x16x32_bf16 v[118:121], v[170:173], v[188:191], v[118:121]
	v_mfma_f32_16x16x32_bf16 v[118:121], v[174:177], v[198:201], v[118:121]
	v_mfma_f32_16x16x32_bf16 v[102:105], v[170:173], v[202:205], v[102:105]
	v_mfma_f32_16x16x32_bf16 v[102:105], v[174:177], v[206:209], v[102:105]
	v_mfma_f32_16x16x32_bf16 v[86:89], v[170:173], v[210:213], v[86:89]
	v_mfma_f32_16x16x32_bf16 v[86:89], v[174:177], v[214:217], v[86:89]
	v_mfma_f32_16x16x32_bf16 v[70:73], v[170:173], v[218:221], v[70:73]
	v_mfma_f32_16x16x32_bf16 v[70:73], v[174:177], v[222:225], v[70:73]
	v_mfma_f32_16x16x32_bf16 v[114:117], v[180:183], v[188:191], v[114:117]
	v_mfma_f32_16x16x32_bf16 v[114:117], v[184:187], v[198:201], v[114:117]
	v_mfma_f32_16x16x32_bf16 v[98:101], v[180:183], v[202:205], v[98:101]
	v_mfma_f32_16x16x32_bf16 v[98:101], v[184:187], v[206:209], v[98:101]
	v_mfma_f32_16x16x32_bf16 v[82:85], v[180:183], v[210:213], v[82:85]
	v_mfma_f32_16x16x32_bf16 v[82:85], v[184:187], v[214:217], v[82:85]
	v_mfma_f32_16x16x32_bf16 v[66:69], v[180:183], v[218:221], v[66:69]
	v_mfma_f32_16x16x32_bf16 v[66:69], v[184:187], v[222:225], v[66:69]
	s_setprio 0
	s_barrier
	s_add_u32 s46, s44, 0x8000
	s_addc_u32 s47, s45, 0
	s_add_i32 s70, s70, s3
	s_mov_b32 m0, s70
	ds_read_b128 v[188:191], v155 offset:49152
	ds_read_b128 v[198:201], v155 offset:50176
	ds_read_b128 v[202:205], v155 offset:51200
	ds_read_b128 v[206:209], v155 offset:52224
	ds_read_b128 v[210:213], v155 offset:53248
	ds_read_b128 v[214:217], v155 offset:54272
	ds_read_b128 v[218:221], v155 offset:55296
	ds_read_b128 v[222:225], v155 offset:56320
	global_load_lds_dwordx4 v132, s[46:47]
	s_add_i32 m0, s70, 0x2000
	s_add_u32 s44, s44, 0xc000
	v_lshl_add_u64 v[226:227], s[46:47], 0, v[136:137]
	s_addc_u32 s45, s45, 0
	s_add_i32 s46, s71, s3
	global_load_lds_dwordx4 v[226:227], off
	s_mov_b32 m0, s46
	s_nop 0
	global_load_lds_dwordx4 v132, s[44:45]
	s_add_i32 m0, s46, 0x2000
	s_nop 0
	global_load_lds_dwordx4 v136, s[44:45]
	s_waitcnt vmcnt(6)
	s_waitcnt lgkmcnt(0)
	s_barrier
	s_setprio 1
	s_waitcnt lgkmcnt(0)
	v_mfma_f32_16x16x32_bf16 v[62:65], v[148:151], v[188:191], v[62:65]
	v_mfma_f32_16x16x32_bf16 v[62:65], v[158:161], v[198:201], v[62:65]
	v_mfma_f32_16x16x32_bf16 v[46:49], v[148:151], v[202:205], v[46:49]
	v_mfma_f32_16x16x32_bf16 v[46:49], v[158:161], v[206:209], v[46:49]
	v_mfma_f32_16x16x32_bf16 v[30:33], v[148:151], v[210:213], v[30:33]
	v_mfma_f32_16x16x32_bf16 v[30:33], v[158:161], v[214:217], v[30:33]
	v_mfma_f32_16x16x32_bf16 v[14:17], v[148:151], v[218:221], v[14:17]
	v_mfma_f32_16x16x32_bf16 v[14:17], v[158:161], v[222:225], v[14:17]
	v_mfma_f32_16x16x32_bf16 v[58:61], v[162:165], v[188:191], v[58:61]
	v_mfma_f32_16x16x32_bf16 v[58:61], v[166:169], v[198:201], v[58:61]
	v_mfma_f32_16x16x32_bf16 v[42:45], v[162:165], v[202:205], v[42:45]
	v_mfma_f32_16x16x32_bf16 v[42:45], v[166:169], v[206:209], v[42:45]
	v_mfma_f32_16x16x32_bf16 v[26:29], v[162:165], v[210:213], v[26:29]
	v_mfma_f32_16x16x32_bf16 v[26:29], v[166:169], v[214:217], v[26:29]
	v_mfma_f32_16x16x32_bf16 v[10:13], v[162:165], v[218:221], v[10:13]
	v_mfma_f32_16x16x32_bf16 v[10:13], v[166:169], v[222:225], v[10:13]
	s_setprio 0
	s_setprio 1
	v_mfma_f32_16x16x32_bf16 v[54:57], v[170:173], v[188:191], v[54:57]
	v_mfma_f32_16x16x32_bf16 v[54:57], v[174:177], v[198:201], v[54:57]
	v_mfma_f32_16x16x32_bf16 v[38:41], v[170:173], v[202:205], v[38:41]
	v_mfma_f32_16x16x32_bf16 v[38:41], v[174:177], v[206:209], v[38:41]
	v_mfma_f32_16x16x32_bf16 v[22:25], v[170:173], v[210:213], v[22:25]
	v_mfma_f32_16x16x32_bf16 v[22:25], v[174:177], v[214:217], v[22:25]
	v_mfma_f32_16x16x32_bf16 v[6:9], v[170:173], v[218:221], v[6:9]
	v_mfma_f32_16x16x32_bf16 v[6:9], v[174:177], v[222:225], v[6:9]
	v_mfma_f32_16x16x32_bf16 v[50:53], v[180:183], v[188:191], v[50:53]
	v_mfma_f32_16x16x32_bf16 v[50:53], v[184:187], v[198:201], v[50:53]
	v_mfma_f32_16x16x32_bf16 v[34:37], v[180:183], v[202:205], v[34:37]
	v_mfma_f32_16x16x32_bf16 v[34:37], v[184:187], v[206:209], v[34:37]
	v_mfma_f32_16x16x32_bf16 v[18:21], v[180:183], v[210:213], v[18:21]
	v_mfma_f32_16x16x32_bf16 v[18:21], v[184:187], v[214:217], v[18:21]
	v_mfma_f32_16x16x32_bf16 v[2:5], v[180:183], v[218:221], v[2:5]
	v_mfma_f32_16x16x32_bf16 v[2:5], v[184:187], v[222:225], v[2:5]
	s_setprio 0
	s_barrier
	s_add_i32 s69, s69, 2
	s_add_u32 s40, s40, 0x10000
	s_addc_u32 s41, s41, 0
	s_add_u32 s67, s67, 0x10000
	s_addc_u32 s68, s68, 0
	s_cmp_gt_u32 s69, 61
	s_cbranch_scc0 .LBB0_840
	s_and_b64 vcc, exec, s[14:15]
	s_cbranch_vccz .LBB0_843
	s_barrier

; #define PG8_STAGE(bufoff, gbase, voff) do { _Pragma("unroll") for (int _i = 0; _i < 2; ++_i) \
;         __builtin_amdgcn_global_load_lds((const unsigned*)((const char*)(gbase) + (voff)[_i]), (PG8_LAS unsigned*)(lds + (bufoff) + ldsw + _i * 8192), 16, 0, 0); } while (0)
; #define PG8_LDA(dst, b, h) do { _Pragma("unroll") for (int m = 0; m < 4; ++m) _Pragma("unroll") for (int k = 0; k < 2; ++k) dst[m][k] = *(const PG8_LAS bf16x8*)(lds + PG8_SA(b, h) + aoff + m * 2048 + k * 1024); } while (0)
; #define PG8_LDB(dst, b, h) do { _Pragma("unroll") for (int n = 0; n < 2; ++n) _Pragma("unroll") for (int k = 0; k < 2; ++k) dst[n][k] = *(const PG8_LAS bf16x8*)(lds + PG8_SB(b, h) + boff + n * 2048 + k * 1024); } while (0)
; #define PG8_MMA(ai, bj, At, Bt) do { __builtin_amdgcn_s_setprio(1); _Pragma("unroll") for (int m = 0; m < 4; ++m) _Pragma("unroll") for (int n = 0; n < 2; ++n) _Pragma("unroll") for (int k = 0; k < 2; ++k) \
;         acc[ai][bj][m][n] = __builtin_amdgcn_mfma_f32_16x16x32_bf16(Bt[n][k], At[m][k], acc[ai][bj][m][n], 0, 0, 0); __builtin_amdgcn_s_setprio(0); } while (0)
; #define PG8_WAIT_V(n) asm volatile("s_waitcnt vmcnt(" #n ")" ::: "memory")
; #define PG8_WAIT_L(n) asm volatile("s_waitcnt lgkmcnt(" #n ")" ::: "memory")
; template <class Epi, class Sched, bool ALIGN_EPI = false, bool SP2 = false>
; __device__ __forceinline__ void gemm_phase(PG8_LAS unsigned char* lds, const Gemm g, const Sched& S, const Epi& E) {
;     ...
;             const bool last = (t == nt - 2);
;             const char* a1 = cA + (size_t)(t + 1) * kstep;
;             const char* a2 = last ? nA : cA + (size_t)(t + 2) * kstep; const char* b2 = last ? nB : cB + (size_t)(t + 2) * kstep;
;             const char* a3 = a2 + kstep; const char* b3 = b2 + kstep;
;             if (last && has_next) S.a_ready(nxt);
;             if constexpr (SP2) {
;             PG8_LDB(B0, 0, 0); PG8_LDB(B1, 0, 1); PG8_SCHED; PG8_LDA(At, 0, 0); PG8_STAGE(PG8_SA(1, 1), a1 + hstep, voffA);
;             PG8_WAIT_V(8); PG8_WAIT_L(0); PG8_BAR; PG8_MMA(0, 0, At, B0); PG8_MMA(0, 1, At, B1); PG8_BAR; PG8_SCHED;
;             PG8_LDA(At, 0, 1); PG8_STAGE(PG8_SB(0, 0), b2, voffB); PG8_STAGE(PG8_SB(0, 1), b2 + hstep, voffB); PG8_STAGE(PG8_SA(0, 0), a2, voffA);
;             PG8_WAIT_V(8); PG8_WAIT_L(0); PG8_BAR; PG8_MMA(1, 0, At, B0); PG8_MMA(1, 1, At, B1); PG8_BAR; PG8_SCHED;
.LBB0_939:
	s_or_b32 s24, s59, 1
	s_lshl_b64 s[62:63], s[24:25], 15
	s_add_i32 s24, s59, 2
	ds_read_b128 v[156:159], v193
	ds_read_b128 v[160:163], v193 offset:1024
	ds_read_b128 v[196:199], v193 offset:2048
	ds_read_b128 v[200:203], v193 offset:3072
	ds_read_b128 v[204:207], v194
	ds_read_b128 v[208:211], v194 offset:1024
	ds_read_b128 v[212:215], v194 offset:2048
	ds_read_b128 v[216:219], v194 offset:3072
	s_lshl_b64 s[8:9], s[24:25], 15
	s_add_u32 s44, s6, s8
	s_addc_u32 s45, s7, s9
	s_cmpk_eq_i32 s59, 0xaa
	s_cselect_b32 s46, s58, s44
	s_cselect_b32 s47, s56, s45
	s_cselect_b32 s44, 0, s8
	s_cselect_b32 s45, 0, s9
	s_add_u32 s8, s46, 0x8000
	s_addc_u32 s9, s47, 0
	s_add_u32 s44, s14, s44
	s_addc_u32 s45, s15, s45
	s_add_u32 s62, s6, s62
	s_addc_u32 s63, s7, s63
	s_add_u32 s62, s62, 0x4000
	s_addc_u32 s63, s63, 0
	s_sub_u32 s8, s62, 0x4000
	s_subb_u32 s9, s63, 0
	s_mov_b32 m0, s51
	s_nop 0
	global_load_lds_dwordx4 v130, s[8:9]
	s_mov_b32 m0, s57
	s_nop 0
	global_load_lds_dwordx4 v134, s[8:9]
	s_add_i32 m0, s30, 0xc000
	ds_read_b128 v[220:223], v186
	ds_read_b128 v[224:227], v186 offset:1024
	ds_read_b128 v[228:231], v186 offset:2048
	ds_read_b128 v[232:235], v186 offset:3072
	ds_read_b128 v[236:239], v186 offset:4096
	ds_read_b128 v[240:243], v186 offset:5120
	ds_read_b128 v[244:247], v186 offset:6144
	ds_read_b128 v[248:251], v186 offset:7168
	global_load_lds_dwordx4 v130, s[62:63]
	s_add_i32 m0, s30, 0xe000
	s_nop 0
	global_load_lds_dwordx4 v134, s[62:63]
	s_waitcnt vmcnt(8)
	s_waitcnt lgkmcnt(0)
	s_barrier
	s_setprio 1
	s_waitcnt lgkmcnt(0)
	v_mfma_f32_16x16x32_bf16 v[126:129], v[156:159], v[220:223], v[126:129]
	v_mfma_f32_16x16x32_bf16 v[126:129], v[160:163], v[224:227], v[126:129]
	v_mfma_f32_16x16x32_bf16 v[110:113], v[156:159], v[228:231], v[110:113]
	v_mfma_f32_16x16x32_bf16 v[110:113], v[160:163], v[232:235], v[110:113]
	v_mfma_f32_16x16x32_bf16 v[94:97], v[156:159], v[236:239], v[94:97]
	v_mfma_f32_16x16x32_bf16 v[94:97], v[160:163], v[240:243], v[94:97]
	v_mfma_f32_16x16x32_bf16 v[78:81], v[156:159], v[244:247], v[78:81]
	v_mfma_f32_16x16x32_bf16 v[78:81], v[160:163], v[248:251], v[78:81]
	v_mfma_f32_16x16x32_bf16 v[122:125], v[196:199], v[220:223], v[122:125]
	v_mfma_f32_16x16x32_bf16 v[122:125], v[200:203], v[224:227], v[122:125]
	v_mfma_f32_16x16x32_bf16 v[106:109], v[196:199], v[228:231], v[106:109]
	v_mfma_f32_16x16x32_bf16 v[106:109], v[200:203], v[232:235], v[106:109]
	v_mfma_f32_16x16x32_bf16 v[90:93], v[196:199], v[236:239], v[90:93]
	v_mfma_f32_16x16x32_bf16 v[90:93], v[200:203], v[240:243], v[90:93]
	v_mfma_f32_16x16x32_bf16 v[74:77], v[196:199], v[244:247], v[74:77]
	v_mfma_f32_16x16x32_bf16 v[74:77], v[200:203], v[248:251], v[74:77]
	s_setprio 0
	s_setprio 1
	v_mfma_f32_16x16x32_bf16 v[118:121], v[204:207], v[220:223], v[118:121]
	v_mfma_f32_16x16x32_bf16 v[118:121], v[208:211], v[224:227], v[118:121]
	v_mfma_f32_16x16x32_bf16 v[102:105], v[204:207], v[228:231], v[102:105]
	v_mfma_f32_16x16x32_bf16 v[102:105], v[208:211], v[232:235], v[102:105]
	v_mfma_f32_16x16x32_bf16 v[86:89], v[204:207], v[236:239], v[86:89]
	v_mfma_f32_16x16x32_bf16 v[86:89], v[208:211], v[240:243], v[86:89]
	v_mfma_f32_16x16x32_bf16 v[70:73], v[204:207], v[244:247], v[70:73]
	v_mfma_f32_16x16x32_bf16 v[70:73], v[208:211], v[248:251], v[70:73]
	v_mfma_f32_16x16x32_bf16 v[114:117], v[212:215], v[220:223], v[114:117]
	v_mfma_f32_16x16x32_bf16 v[114:117], v[216:219], v[224:227], v[114:117]
	v_mfma_f32_16x16x32_bf16 v[98:101], v[212:215], v[228:231], v[98:101]
	v_mfma_f32_16x16x32_bf16 v[98:101], v[216:219], v[232:235], v[98:101]
	v_mfma_f32_16x16x32_bf16 v[82:85], v[212:215], v[236:239], v[82:85]
	v_mfma_f32_16x16x32_bf16 v[82:85], v[216:219], v[240:243], v[82:85]
	v_mfma_f32_16x16x32_bf16 v[66:69], v[212:215], v[244:247], v[66:69]
	v_mfma_f32_16x16x32_bf16 v[66:69], v[216:219], v[248:251], v[66:69]
	s_setprio 0
	s_barrier
	s_add_i32 s62, s67, s29
	s_mov_b32 m0, s62
	ds_read_b128 v[220:223], v186 offset:16384
	ds_read_b128 v[224:227], v186 offset:17408
	ds_read_b128 v[228:231], v186 offset:18432
	ds_read_b128 v[232:235], v186 offset:19456
	ds_read_b128 v[236:239], v186 offset:20480
	ds_read_b128 v[240:243], v186 offset:21504
	ds_read_b128 v[244:247], v186 offset:22528
	ds_read_b128 v[248:251], v186 offset:23552
	global_load_lds_dwordx4 v132, s[44:45]
	s_add_i32 m0, s62, 0x2000
	s_add_u32 s62, s44, 0x4000
	v_lshl_add_u64 v[164:165], s[44:45], 0, v[136:137]
	s_addc_u32 s63, s45, 0
	s_add_i32 s72, s68, s29
	global_load_lds_dwordx4 v[164:165], off
	s_mov_b32 m0, s72
	s_nop 0
	global_load_lds_dwordx4 v132, s[62:63]
	s_add_i32 m0, s72, 0x2000
	s_nop 0
	global_load_lds_dwordx4 v136, s[62:63]
	s_waitcnt vmcnt(6)
	s_waitcnt lgkmcnt(0)
	s_barrier
; #define PG8_STAGE(bufoff, gbase, voff) do { _Pragma("unroll") for (int _i = 0; _i < 2; ++_i) \
;         __builtin_amdgcn_global_load_lds((const unsigned*)((const char*)(gbase) + (voff)[_i]), (PG8_LAS unsigned*)(lds + (bufoff) + ldsw + _i * 8192), 16, 0, 0); } while (0)
; #define PG8_LDA(dst, b, h) do { _Pragma("unroll") for (int m = 0; m < 4; ++m) _Pragma("unroll") for (int k = 0; k < 2; ++k) dst[m][k] = *(const PG8_LAS bf16x8*)(lds + PG8_SA(b, h) + aoff + m * 2048 + k * 1024); } while (0)
; #define PG8_LDB(dst, b, h) do { _Pragma("unroll") for (int n = 0; n < 2; ++n) _Pragma("unroll") for (int k = 0; k < 2; ++k) dst[n][k] = *(const PG8_LAS bf16x8*)(lds + PG8_SB(b, h) + boff + n * 2048 + k * 1024); } while (0)
; #define PG8_MMA(ai, bj, At, Bt) do { __builtin_amdgcn_s_setprio(1); _Pragma("unroll") for (int m = 0; m < 4; ++m) _Pragma("unroll") for (int n = 0; n < 2; ++n) _Pragma("unroll") for (int k = 0; k < 2; ++k) \
;         acc[ai][bj][m][n] = __builtin_amdgcn_mfma_f32_16x16x32_bf16(Bt[n][k], At[m][k], acc[ai][bj][m][n], 0, 0, 0); __builtin_amdgcn_s_setprio(0); } while (0)
; #define PG8_WAIT_V(n) asm volatile("s_waitcnt vmcnt(" #n ")" ::: "memory")
; #define PG8_WAIT_L(n) asm volatile("s_waitcnt lgkmcnt(" #n ")" ::: "memory")
; #define PG8_BAR __builtin_amdgcn_s_barrier()
; #define PG8_SCHED __builtin_amdgcn_sched_barrier(0)
; template <class Epi, class Sched, bool ALIGN_EPI = false, bool SP2 = false>
; __device__ __forceinline__ void gemm_phase(PG8_LAS unsigned char* lds, const Gemm g, const Sched& S, const Epi& E) {
;     ...
;             PG8_WAIT_V(8); PG8_WAIT_L(0); PG8_BAR; PG8_MMA(1, 0, At, B0); PG8_MMA(1, 1, At, B1); PG8_BAR; PG8_SCHED;
;             PG8_LDB(B0, 1, 0); PG8_LDB(B1, 1, 1); PG8_SCHED; PG8_LDA(At, 1, 0); PG8_STAGE(PG8_SA(0, 1), a2 + hstep, voffA);
;             PG8_WAIT_V(8); PG8_WAIT_L(0); PG8_BAR; PG8_MMA(0, 0, At, B0); PG8_MMA(0, 1, At, B1); PG8_BAR; PG8_SCHED;
	s_setprio 1
	s_waitcnt lgkmcnt(0)
	v_mfma_f32_16x16x32_bf16 v[62:65], v[156:159], v[220:223], v[62:65]
	v_mfma_f32_16x16x32_bf16 v[62:65], v[160:163], v[224:227], v[62:65]
	v_mfma_f32_16x16x32_bf16 v[46:49], v[156:159], v[228:231], v[46:49]
	v_mfma_f32_16x16x32_bf16 v[46:49], v[160:163], v[232:235], v[46:49]
	v_mfma_f32_16x16x32_bf16 v[30:33], v[156:159], v[236:239], v[30:33]
	v_mfma_f32_16x16x32_bf16 v[30:33], v[160:163], v[240:243], v[30:33]
	v_mfma_f32_16x16x32_bf16 v[14:17], v[156:159], v[244:247], v[14:17]
	v_mfma_f32_16x16x32_bf16 v[14:17], v[160:163], v[248:251], v[14:17]
	v_mfma_f32_16x16x32_bf16 v[58:61], v[196:199], v[220:223], v[58:61]
	v_mfma_f32_16x16x32_bf16 v[58:61], v[200:203], v[224:227], v[58:61]
	v_mfma_f32_16x16x32_bf16 v[42:45], v[196:199], v[228:231], v[42:45]
	v_mfma_f32_16x16x32_bf16 v[42:45], v[200:203], v[232:235], v[42:45]
	v_mfma_f32_16x16x32_bf16 v[26:29], v[196:199], v[236:239], v[26:29]
	v_mfma_f32_16x16x32_bf16 v[26:29], v[200:203], v[240:243], v[26:29]
	v_mfma_f32_16x16x32_bf16 v[10:13], v[196:199], v[244:247], v[10:13]
	v_mfma_f32_16x16x32_bf16 v[10:13], v[200:203], v[248:251], v[10:13]
	s_setprio 0
	s_setprio 1
	v_mfma_f32_16x16x32_bf16 v[54:57], v[204:207], v[220:223], v[54:57]
	v_mfma_f32_16x16x32_bf16 v[54:57], v[208:211], v[224:227], v[54:57]
	v_mfma_f32_16x16x32_bf16 v[38:41], v[204:207], v[228:231], v[38:41]
	v_mfma_f32_16x16x32_bf16 v[38:41], v[208:211], v[232:235], v[38:41]
	v_mfma_f32_16x16x32_bf16 v[22:25], v[204:207], v[236:239], v[22:25]
	v_mfma_f32_16x16x32_bf16 v[22:25], v[208:211], v[240:243], v[22:25]
	v_mfma_f32_16x16x32_bf16 v[6:9], v[204:207], v[244:247], v[6:9]
	v_mfma_f32_16x16x32_bf16 v[6:9], v[208:211], v[248:251], v[6:9]
	v_mfma_f32_16x16x32_bf16 v[50:53], v[212:215], v[220:223], v[50:53]
	v_mfma_f32_16x16x32_bf16 v[50:53], v[216:219], v[224:227], v[50:53]
	v_mfma_f32_16x16x32_bf16 v[34:37], v[212:215], v[228:231], v[34:37]
	v_mfma_f32_16x16x32_bf16 v[34:37], v[216:219], v[232:235], v[34:37]
	v_mfma_f32_16x16x32_bf16 v[18:21], v[212:215], v[236:239], v[18:21]
	v_mfma_f32_16x16x32_bf16 v[18:21], v[216:219], v[240:243], v[18:21]
	v_mfma_f32_16x16x32_bf16 v[2:5], v[212:215], v[244:247], v[2:5]
	v_mfma_f32_16x16x32_bf16 v[2:5], v[216:219], v[248:251], v[2:5]
	s_setprio 0
	s_barrier
	s_add_i32 s62, 0, 0x18000
	v_add_u32_e32 v145, s62, v166
	s_add_i32 s63, 0, 0x1c000
	ds_read_b128 v[156:159], v145
	ds_read_b128 v[160:163], v145 offset:1024
	ds_read_b128 v[196:199], v145 offset:2048
	ds_read_b128 v[200:203], v145 offset:3072
	v_add_u32_e32 v145, s63, v166
	ds_read_b128 v[204:207], v145
	ds_read_b128 v[208:211], v145 offset:1024
	ds_read_b128 v[212:215], v145 offset:2048
	ds_read_b128 v[216:219], v145 offset:3072
	s_mov_b32 m0, s30
	s_nop 0
	global_load_lds_dwordx4 v130, s[46:47]
	s_mov_b32 m0, s31
	s_nop 0
	global_load_lds_dwordx4 v134, s[46:47]
	s_add_u32 s46, s46, 0x4000
	s_addc_u32 s47, s47, 0
	s_mov_b32 m0, s35
	ds_read_b128 v[220:223], v186 offset:32768
	ds_read_b128 v[224:227], v186 offset:33792
	ds_read_b128 v[228:231], v186 offset:34816
	ds_read_b128 v[232:235], v186 offset:35840
	ds_read_b128 v[236:239], v186 offset:36864
	ds_read_b128 v[240:243], v186 offset:37888
	ds_read_b128 v[244:247], v186 offset:38912
	ds_read_b128 v[248:251], v186 offset:39936
	global_load_lds_dwordx4 v130, s[46:47]
	s_mov_b32 m0, s48
	s_nop 0
	global_load_lds_dwordx4 v134, s[46:47]
	s_waitcnt vmcnt(8)
	s_waitcnt lgkmcnt(0)
	s_barrier
; #define PG8_STAGE(bufoff, gbase, voff) do { _Pragma("unroll") for (int _i = 0; _i < 2; ++_i) \
;         __builtin_amdgcn_global_load_lds((const unsigned*)((const char*)(gbase) + (voff)[_i]), (PG8_LAS unsigned*)(lds + (bufoff) + ldsw + _i * 8192), 16, 0, 0); } while (0)
; #define PG8_LDA(dst, b, h) do { _Pragma("unroll") for (int m = 0; m < 4; ++m) _Pragma("unroll") for (int k = 0; k < 2; ++k) dst[m][k] = *(const PG8_LAS bf16x8*)(lds + PG8_SA(b, h) + aoff + m * 2048 + k * 1024); } while (0)
; #define PG8_MMA(ai, bj, At, Bt) do { __builtin_amdgcn_s_setprio(1); _Pragma("unroll") for (int m = 0; m < 4; ++m) _Pragma("unroll") for (int n = 0; n < 2; ++n) _Pragma("unroll") for (int k = 0; k < 2; ++k) \
;         acc[ai][bj][m][n] = __builtin_amdgcn_mfma_f32_16x16x32_bf16(Bt[n][k], At[m][k], acc[ai][bj][m][n], 0, 0, 0); __builtin_amdgcn_s_setprio(0); } while (0)
; #define PG8_WAIT_V(n) asm volatile("s_waitcnt vmcnt(" #n ")" ::: "memory")
; #define PG8_WAIT_L(n) asm volatile("s_waitcnt lgkmcnt(" #n ")" ::: "memory")
; #define PG8_BAR __builtin_amdgcn_s_barrier()
; #define PG8_SCHED __builtin_amdgcn_sched_barrier(0)
; template <class Epi, class Sched, bool ALIGN_EPI = false, bool SP2 = false>
; __device__ __forceinline__ void gemm_phase(PG8_LAS unsigned char* lds, const Gemm g, const Sched& S, const Epi& E) {
;     ...
;         for (; t < tend; t += 2) {
;     ...
;             PG8_WAIT_V(8); PG8_WAIT_L(0); PG8_BAR; PG8_MMA(0, 0, At, B0); PG8_MMA(0, 1, At, B1); PG8_BAR; PG8_SCHED;
;             PG8_LDA(At, 1, 1); PG8_STAGE(PG8_SB(1, 0), b3, voffB); PG8_STAGE(PG8_SB(1, 1), b3 + hstep, voffB); PG8_STAGE(PG8_SA(1, 0), a3, voffA);
;             PG8_WAIT_V(8); PG8_WAIT_L(0); PG8_BAR; PG8_MMA(1, 0, At, B0); PG8_MMA(1, 1, At, B1); PG8_BAR; PG8_SCHED;
	s_setprio 1
	s_waitcnt lgkmcnt(0)
	v_mfma_f32_16x16x32_bf16 v[126:129], v[156:159], v[220:223], v[126:129]
	v_mfma_f32_16x16x32_bf16 v[126:129], v[160:163], v[224:227], v[126:129]
	v_mfma_f32_16x16x32_bf16 v[110:113], v[156:159], v[228:231], v[110:113]
	v_mfma_f32_16x16x32_bf16 v[110:113], v[160:163], v[232:235], v[110:113]
	v_mfma_f32_16x16x32_bf16 v[94:97], v[156:159], v[236:239], v[94:97]
	v_mfma_f32_16x16x32_bf16 v[94:97], v[160:163], v[240:243], v[94:97]
	v_mfma_f32_16x16x32_bf16 v[78:81], v[156:159], v[244:247], v[78:81]
	v_mfma_f32_16x16x32_bf16 v[78:81], v[160:163], v[248:251], v[78:81]
	v_mfma_f32_16x16x32_bf16 v[122:125], v[196:199], v[220:223], v[122:125]
	v_mfma_f32_16x16x32_bf16 v[122:125], v[200:203], v[224:227], v[122:125]
	v_mfma_f32_16x16x32_bf16 v[106:109], v[196:199], v[228:231], v[106:109]
	v_mfma_f32_16x16x32_bf16 v[106:109], v[200:203], v[232:235], v[106:109]
	v_mfma_f32_16x16x32_bf16 v[90:93], v[196:199], v[236:239], v[90:93]
	v_mfma_f32_16x16x32_bf16 v[90:93], v[200:203], v[240:243], v[90:93]
	v_mfma_f32_16x16x32_bf16 v[74:77], v[196:199], v[244:247], v[74:77]
	v_mfma_f32_16x16x32_bf16 v[74:77], v[200:203], v[248:251], v[74:77]
	s_setprio 0
	s_setprio 1
	v_mfma_f32_16x16x32_bf16 v[118:121], v[204:207], v[220:223], v[118:121]
	v_mfma_f32_16x16x32_bf16 v[118:121], v[208:211], v[224:227], v[118:121]
	v_mfma_f32_16x16x32_bf16 v[102:105], v[204:207], v[228:231], v[102:105]
	v_mfma_f32_16x16x32_bf16 v[102:105], v[208:211], v[232:235], v[102:105]
	v_mfma_f32_16x16x32_bf16 v[86:89], v[204:207], v[236:239], v[86:89]
	v_mfma_f32_16x16x32_bf16 v[86:89], v[208:211], v[240:243], v[86:89]
	v_mfma_f32_16x16x32_bf16 v[70:73], v[204:207], v[244:247], v[70:73]
	v_mfma_f32_16x16x32_bf16 v[70:73], v[208:211], v[248:251], v[70:73]
	v_mfma_f32_16x16x32_bf16 v[114:117], v[212:215], v[220:223], v[114:117]
	v_mfma_f32_16x16x32_bf16 v[114:117], v[216:219], v[224:227], v[114:117]
	v_mfma_f32_16x16x32_bf16 v[98:101], v[212:215], v[228:231], v[98:101]
	v_mfma_f32_16x16x32_bf16 v[98:101], v[216:219], v[232:235], v[98:101]
	v_mfma_f32_16x16x32_bf16 v[82:85], v[212:215], v[236:239], v[82:85]
	v_mfma_f32_16x16x32_bf16 v[82:85], v[216:219], v[240:243], v[82:85]
	v_mfma_f32_16x16x32_bf16 v[66:69], v[212:215], v[244:247], v[66:69]
	v_mfma_f32_16x16x32_bf16 v[66:69], v[216:219], v[248:251], v[66:69]
	s_setprio 0
	s_barrier
	s_add_u32 s46, s44, 0x8000
	s_addc_u32 s47, s45, 0
	s_add_i32 s62, s62, s29
	s_mov_b32 m0, s62
	ds_read_b128 v[220:223], v186 offset:49152
	ds_read_b128 v[224:227], v186 offset:50176
	ds_read_b128 v[228:231], v186 offset:51200
	ds_read_b128 v[232:235], v186 offset:52224
	ds_read_b128 v[236:239], v186 offset:53248
	ds_read_b128 v[240:243], v186 offset:54272
	ds_read_b128 v[244:247], v186 offset:55296
	ds_read_b128 v[248:251], v186 offset:56320
	global_load_lds_dwordx4 v132, s[46:47]
	s_add_i32 m0, s62, 0x2000
	s_add_u32 s44, s44, 0xc000
	v_lshl_add_u64 v[164:165], s[46:47], 0, v[136:137]
	s_addc_u32 s45, s45, 0
	s_add_i32 s46, s63, s29
	global_load_lds_dwordx4 v[164:165], off
	s_mov_b32 m0, s46
	s_nop 0
	global_load_lds_dwordx4 v132, s[44:45]
	s_add_i32 m0, s46, 0x2000
	s_nop 0
	global_load_lds_dwordx4 v136, s[44:45]
	s_waitcnt vmcnt(6)
	s_waitcnt lgkmcnt(0)
	s_barrier
	s_setprio 1
	s_waitcnt lgkmcnt(0)
	v_mfma_f32_16x16x32_bf16 v[62:65], v[156:159], v[220:223], v[62:65]
	v_mfma_f32_16x16x32_bf16 v[62:65], v[160:163], v[224:227], v[62:65]
	v_mfma_f32_16x16x32_bf16 v[46:49], v[156:159], v[228:231], v[46:49]
	v_mfma_f32_16x16x32_bf16 v[46:49], v[160:163], v[232:235], v[46:49]
	v_mfma_f32_16x16x32_bf16 v[30:33], v[156:159], v[236:239], v[30:33]
	v_mfma_f32_16x16x32_bf16 v[30:33], v[160:163], v[240:243], v[30:33]
	v_mfma_f32_16x16x32_bf16 v[14:17], v[156:159], v[244:247], v[14:17]
	v_mfma_f32_16x16x32_bf16 v[14:17], v[160:163], v[248:251], v[14:17]
	v_mfma_f32_16x16x32_bf16 v[58:61], v[196:199], v[220:223], v[58:61]
	v_mfma_f32_16x16x32_bf16 v[58:61], v[200:203], v[224:227], v[58:61]
	v_mfma_f32_16x16x32_bf16 v[42:45], v[196:199], v[228:231], v[42:45]
	v_mfma_f32_16x16x32_bf16 v[42:45], v[200:203], v[232:235], v[42:45]
	v_mfma_f32_16x16x32_bf16 v[26:29], v[196:199], v[236:239], v[26:29]
	v_mfma_f32_16x16x32_bf16 v[26:29], v[200:203], v[240:243], v[26:29]
	v_mfma_f32_16x16x32_bf16 v[10:13], v[196:199], v[244:247], v[10:13]
	v_mfma_f32_16x16x32_bf16 v[10:13], v[200:203], v[248:251], v[10:13]
	s_setprio 0
	s_setprio 1
	v_mfma_f32_16x16x32_bf16 v[54:57], v[204:207], v[220:223], v[54:57]
	v_mfma_f32_16x16x32_bf16 v[54:57], v[208:211], v[224:227], v[54:57]
	v_mfma_f32_16x16x32_bf16 v[38:41], v[204:207], v[228:231], v[38:41]
	v_mfma_f32_16x16x32_bf16 v[38:41], v[208:211], v[232:235], v[38:41]
	v_mfma_f32_16x16x32_bf16 v[22:25], v[204:207], v[236:239], v[22:25]
	v_mfma_f32_16x16x32_bf16 v[22:25], v[208:211], v[240:243], v[22:25]
	v_mfma_f32_16x16x32_bf16 v[6:9], v[204:207], v[244:247], v[6:9]
	v_mfma_f32_16x16x32_bf16 v[6:9], v[208:211], v[248:251], v[6:9]
	v_mfma_f32_16x16x32_bf16 v[50:53], v[212:215], v[220:223], v[50:53]
	v_mfma_f32_16x16x32_bf16 v[50:53], v[216:219], v[224:227], v[50:53]
	v_mfma_f32_16x16x32_bf16 v[34:37], v[212:215], v[228:231], v[34:37]
	v_mfma_f32_16x16x32_bf16 v[34:37], v[216:219], v[232:235], v[34:37]
	v_mfma_f32_16x16x32_bf16 v[18:21], v[212:215], v[236:239], v[18:21]
	v_mfma_f32_16x16x32_bf16 v[18:21], v[216:219], v[240:243], v[18:21]
	v_mfma_f32_16x16x32_bf16 v[2:5], v[212:215], v[244:247], v[2:5]
	v_mfma_f32_16x16x32_bf16 v[2:5], v[216:219], v[248:251], v[2:5]
	s_setprio 0
	s_barrier
	s_cmpk_gt_u32 s59, 0xa9
	s_mov_b32 s59, s24
	s_cbranch_scc0 .LBB0_939
	s_and_b64 vcc, exec, s[38:39]
	s_cbranch_vccz .LBB0_942
	s_barrier
